# GEMM K-loops: removed the mid-block s_setprio 0/1 pair so each 32-MFMA block issues contiguously (bytes re-added after the loop)
# baseline (speedup 1.0000x reference)
.LBB0_116:
	ds_read_b128 v[50:53], v185
	ds_read_b128 v[54:57], v185 offset:1024
	ds_read_b128 v[138:141], v185 offset:2048
	ds_read_b128 v[142:145], v185 offset:3072
	ds_read_b128 v[168:171], v189
	ds_read_b128 v[174:177], v189 offset:1024
	ds_read_b128 v[194:197], v189 offset:2048
	ds_read_b128 v[198:201], v189 offset:3072
	s_add_u32 s60, s52, 0xfff80080
	s_addc_u32 s61, s53, -1
	s_cmp_eq_u32 s64, 28
	s_cselect_b32 s63, s33, s61
	s_cselect_b32 s62, s34, s60
	s_cselect_b32 s61, s35, s51
	s_cselect_b32 s60, s41, s43
	v_lshl_add_u64 v[178:179], s[52:53], 0, v[158:159]
	s_add_i32 m0, s16, 0xc000
	ds_read_b128 v[202:205], v193
	ds_read_b128 v[206:209], v193 offset:1024
	ds_read_b128 v[210:213], v193 offset:2048
	ds_read_b128 v[214:217], v193 offset:3072
	ds_read_b128 v[218:221], v193 offset:4096
	ds_read_b128 v[222:225], v193 offset:5120
	ds_read_b128 v[226:229], v193 offset:6144
	ds_read_b128 v[230:233], v193 offset:7168
	global_load_lds_dwordx4 v[178:179], off
	v_lshl_add_u64 v[178:179], s[52:53], 0, v[160:161]
	s_add_i32 m0, s16, 0xe000
	s_nop 0
	global_load_lds_dwordx4 v[178:179], off
	s_waitcnt vmcnt(8)
	s_waitcnt lgkmcnt(0)
	s_barrier
	s_setprio 1
	s_waitcnt lgkmcnt(0)
	v_mfma_i32_16x16x64_i8 v[134:137], v[50:53], v[202:205], v[134:137]
	v_mfma_i32_16x16x64_i8 v[130:133], v[138:141], v[202:205], v[130:133]
	v_mfma_i32_16x16x64_i8 v[118:121], v[50:53], v[210:213], v[118:121]
	v_mfma_i32_16x16x64_i8 v[114:117], v[138:141], v[210:213], v[114:117]
	v_mfma_i32_16x16x64_i8 v[102:105], v[50:53], v[218:221], v[102:105]
	v_mfma_i32_16x16x64_i8 v[98:101], v[138:141], v[218:221], v[98:101]
	v_mfma_i32_16x16x64_i8 v[86:89], v[50:53], v[226:229], v[86:89]
	v_mfma_i32_16x16x64_i8 v[82:85], v[138:141], v[226:229], v[82:85]
	v_mfma_i32_16x16x64_i8 v[134:137], v[54:57], v[206:209], v[134:137]
	v_mfma_i32_16x16x64_i8 v[130:133], v[142:145], v[206:209], v[130:133]
	v_mfma_i32_16x16x64_i8 v[118:121], v[54:57], v[214:217], v[118:121]
	v_mfma_i32_16x16x64_i8 v[114:117], v[142:145], v[214:217], v[114:117]
	v_mfma_i32_16x16x64_i8 v[102:105], v[54:57], v[222:225], v[102:105]
	v_mfma_i32_16x16x64_i8 v[98:101], v[142:145], v[222:225], v[98:101]
	v_mfma_i32_16x16x64_i8 v[86:89], v[54:57], v[230:233], v[86:89]
	v_mfma_i32_16x16x64_i8 v[82:85], v[142:145], v[230:233], v[82:85]
	v_mfma_i32_16x16x64_i8 v[126:129], v[168:171], v[202:205], v[126:129]
	v_mfma_i32_16x16x64_i8 v[122:125], v[194:197], v[202:205], v[122:125]
	v_mfma_i32_16x16x64_i8 v[110:113], v[168:171], v[210:213], v[110:113]
	v_mfma_i32_16x16x64_i8 v[106:109], v[194:197], v[210:213], v[106:109]
	v_mfma_i32_16x16x64_i8 v[94:97], v[168:171], v[218:221], v[94:97]
	v_mfma_i32_16x16x64_i8 v[90:93], v[194:197], v[218:221], v[90:93]
	v_mfma_i32_16x16x64_i8 v[78:81], v[168:171], v[226:229], v[78:81]
	v_mfma_i32_16x16x64_i8 v[74:77], v[194:197], v[226:229], v[74:77]
	v_mfma_i32_16x16x64_i8 v[126:129], v[174:177], v[206:209], v[126:129]
	v_mfma_i32_16x16x64_i8 v[122:125], v[198:201], v[206:209], v[122:125]
	v_mfma_i32_16x16x64_i8 v[110:113], v[174:177], v[214:217], v[110:113]
	v_mfma_i32_16x16x64_i8 v[106:109], v[198:201], v[214:217], v[106:109]
	v_mfma_i32_16x16x64_i8 v[94:97], v[174:177], v[222:225], v[94:97]
	v_mfma_i32_16x16x64_i8 v[90:93], v[198:201], v[222:225], v[90:93]
	v_mfma_i32_16x16x64_i8 v[78:81], v[174:177], v[230:233], v[78:81]
	v_mfma_i32_16x16x64_i8 v[74:77], v[198:201], v[230:233], v[74:77]
	s_setprio 0
	s_barrier
	s_add_i32 s65, s24, s14
	v_lshl_add_u64 v[178:179], s[60:61], 0, v[150:151]
	s_mov_b32 m0, s65
	ds_read_b128 v[202:205], v193 offset:16384
	ds_read_b128 v[206:209], v193 offset:17408
	ds_read_b128 v[210:213], v193 offset:18432
	ds_read_b128 v[214:217], v193 offset:19456
	ds_read_b128 v[218:221], v193 offset:20480
	ds_read_b128 v[222:225], v193 offset:21504
	ds_read_b128 v[226:229], v193 offset:22528
	ds_read_b128 v[230:233], v193 offset:23552
	global_load_lds_dwordx4 v[178:179], off
	s_add_i32 m0, s65, 0x2000
	s_add_u32 s66, s60, 0x80000
	v_lshl_add_u64 v[182:183], s[60:61], 0, v[146:147]
	s_addc_u32 s67, s61, 0
	s_add_i32 s65, s25, s14
	global_load_lds_dwordx4 v[182:183], off
	v_lshl_add_u64 v[186:187], s[66:67], 0, v[150:151]
	s_mov_b32 m0, s65
	v_lshl_add_u64 v[190:191], s[62:63], 0, v[148:149]
	global_load_lds_dwordx4 v[186:187], off
	v_lshl_add_u64 v[186:187], s[66:67], 0, v[146:147]
	s_add_i32 m0, s65, 0x2000
	s_nop 0
	global_load_lds_dwordx4 v[186:187], off
	v_lshl_add_u64 v[186:187], s[62:63], 0, v[152:153]
	s_mov_b32 m0, s16
	s_nop 0
	global_load_lds_dwordx4 v[186:187], off
	s_mov_b32 m0, s17
	s_nop 0
	global_load_lds_dwordx4 v[190:191], off
	s_waitcnt vmcnt(8)
	s_waitcnt lgkmcnt(0)
	s_barrier
	s_setprio 1
	s_waitcnt lgkmcnt(0)
	v_mfma_i32_16x16x64_i8 v[70:73], v[50:53], v[202:205], v[70:73]
	v_mfma_i32_16x16x64_i8 v[66:69], v[138:141], v[202:205], v[66:69]
	v_mfma_i32_16x16x64_i8 v[46:49], v[50:53], v[210:213], v[46:49]
	v_mfma_i32_16x16x64_i8 v[42:45], v[138:141], v[210:213], v[42:45]
	v_mfma_i32_16x16x64_i8 v[30:33], v[50:53], v[218:221], v[30:33]
	v_mfma_i32_16x16x64_i8 v[26:29], v[138:141], v[218:221], v[26:29]
	v_mfma_i32_16x16x64_i8 v[14:17], v[50:53], v[226:229], v[14:17]
	v_mfma_i32_16x16x64_i8 v[10:13], v[138:141], v[226:229], v[10:13]
	v_mfma_i32_16x16x64_i8 v[70:73], v[54:57], v[206:209], v[70:73]
	v_mfma_i32_16x16x64_i8 v[66:69], v[142:145], v[206:209], v[66:69]
	v_mfma_i32_16x16x64_i8 v[46:49], v[54:57], v[214:217], v[46:49]
	v_mfma_i32_16x16x64_i8 v[42:45], v[142:145], v[214:217], v[42:45]
	v_mfma_i32_16x16x64_i8 v[30:33], v[54:57], v[222:225], v[30:33]
	v_mfma_i32_16x16x64_i8 v[26:29], v[142:145], v[222:225], v[26:29]
	v_mfma_i32_16x16x64_i8 v[14:17], v[54:57], v[230:233], v[14:17]
	v_mfma_i32_16x16x64_i8 v[10:13], v[142:145], v[230:233], v[10:13]
	v_mfma_i32_16x16x64_i8 v[38:41], v[168:171], v[210:213], v[38:41]
	v_mfma_i32_16x16x64_i8 v[34:37], v[194:197], v[210:213], v[34:37]
	v_mfma_i32_16x16x64_i8 v[22:25], v[168:171], v[218:221], v[22:25]
	v_mfma_i32_16x16x64_i8 v[18:21], v[194:197], v[218:221], v[18:21]
	v_mfma_i32_16x16x64_i8 v[6:9], v[168:171], v[226:229], v[6:9]
	v_mfma_i32_16x16x64_i8 v[2:5], v[194:197], v[226:229], v[2:5]
	v_mfma_i32_16x16x64_i8 v[50:53], v[168:171], v[202:205], v[62:65]
	v_mfma_i32_16x16x64_i8 v[54:57], v[194:197], v[202:205], v[58:61]
	v_mfma_i32_16x16x64_i8 v[38:41], v[174:177], v[214:217], v[38:41]
	v_mfma_i32_16x16x64_i8 v[34:37], v[198:201], v[214:217], v[34:37]
	v_mfma_i32_16x16x64_i8 v[22:25], v[174:177], v[222:225], v[22:25]
	v_mfma_i32_16x16x64_i8 v[18:21], v[198:201], v[222:225], v[18:21]
	v_mfma_i32_16x16x64_i8 v[6:9], v[174:177], v[230:233], v[6:9]
	v_mfma_i32_16x16x64_i8 v[2:5], v[198:201], v[230:233], v[2:5]
	v_mfma_i32_16x16x64_i8 v[50:53], v[174:177], v[206:209], v[50:53]
	v_mfma_i32_16x16x64_i8 v[54:57], v[198:201], v[206:209], v[54:57]
	s_setprio 0
	s_barrier
	s_add_i32 s65, 0, 0x18000
	s_add_i32 s66, 0, 0x1c000
	v_add_u32_e32 v142, s65, v173
	v_add_u32_e32 v154, s66, v173
	ds_read_b128 v[58:61], v142
	ds_read_b128 v[62:65], v142 offset:1024
	ds_read_b128 v[138:141], v142 offset:2048
	ds_read_b128 v[142:145], v142 offset:3072
	ds_read_b128 v[168:171], v154
	ds_read_b128 v[174:177], v154 offset:1024
	ds_read_b128 v[194:197], v154 offset:2048
	ds_read_b128 v[198:201], v154 offset:3072
	s_add_u32 s62, s62, 0x80000
	s_addc_u32 s63, s63, 0
	s_mov_b32 m0, s18
	v_lshl_add_u64 v[234:235], s[62:63], 0, v[152:153]
	ds_read_b128 v[202:205], v193 offset:32768
	ds_read_b128 v[206:209], v193 offset:33792
	ds_read_b128 v[210:213], v193 offset:34816
	ds_read_b128 v[214:217], v193 offset:35840
	ds_read_b128 v[218:221], v193 offset:36864
	ds_read_b128 v[222:225], v193 offset:37888
	ds_read_b128 v[226:229], v193 offset:38912
	ds_read_b128 v[230:233], v193 offset:39936
	global_load_lds_dwordx4 v[234:235], off
	v_lshl_add_u64 v[234:235], s[62:63], 0, v[148:149]
	s_mov_b32 m0, s19
	s_nop 0
	global_load_lds_dwordx4 v[234:235], off
	s_waitcnt vmcnt(8)
	s_waitcnt lgkmcnt(0)
	s_barrier
	s_setprio 1
	s_waitcnt lgkmcnt(0)
	v_mfma_i32_16x16x64_i8 v[134:137], v[58:61], v[202:205], v[134:137]
	v_mfma_i32_16x16x64_i8 v[130:133], v[138:141], v[202:205], v[130:133]
	v_mfma_i32_16x16x64_i8 v[118:121], v[58:61], v[210:213], v[118:121]
	v_mfma_i32_16x16x64_i8 v[114:117], v[138:141], v[210:213], v[114:117]
	v_mfma_i32_16x16x64_i8 v[102:105], v[58:61], v[218:221], v[102:105]
	v_mfma_i32_16x16x64_i8 v[98:101], v[138:141], v[218:221], v[98:101]
	v_mfma_i32_16x16x64_i8 v[86:89], v[58:61], v[226:229], v[86:89]
	v_mfma_i32_16x16x64_i8 v[82:85], v[138:141], v[226:229], v[82:85]
	v_mfma_i32_16x16x64_i8 v[134:137], v[62:65], v[206:209], v[134:137]
	v_mfma_i32_16x16x64_i8 v[130:133], v[142:145], v[206:209], v[130:133]
	v_mfma_i32_16x16x64_i8 v[118:121], v[62:65], v[214:217], v[118:121]
	v_mfma_i32_16x16x64_i8 v[114:117], v[142:145], v[214:217], v[114:117]
	v_mfma_i32_16x16x64_i8 v[102:105], v[62:65], v[222:225], v[102:105]
	v_mfma_i32_16x16x64_i8 v[98:101], v[142:145], v[222:225], v[98:101]
	v_mfma_i32_16x16x64_i8 v[86:89], v[62:65], v[230:233], v[86:89]
	v_mfma_i32_16x16x64_i8 v[82:85], v[142:145], v[230:233], v[82:85]
	v_mfma_i32_16x16x64_i8 v[126:129], v[168:171], v[202:205], v[126:129]
	v_mfma_i32_16x16x64_i8 v[122:125], v[194:197], v[202:205], v[122:125]
	v_mfma_i32_16x16x64_i8 v[110:113], v[168:171], v[210:213], v[110:113]
	v_mfma_i32_16x16x64_i8 v[106:109], v[194:197], v[210:213], v[106:109]
	v_mfma_i32_16x16x64_i8 v[94:97], v[168:171], v[218:221], v[94:97]
	v_mfma_i32_16x16x64_i8 v[90:93], v[194:197], v[218:221], v[90:93]
	v_mfma_i32_16x16x64_i8 v[78:81], v[168:171], v[226:229], v[78:81]
	v_mfma_i32_16x16x64_i8 v[74:77], v[194:197], v[226:229], v[74:77]
	v_mfma_i32_16x16x64_i8 v[126:129], v[174:177], v[206:209], v[126:129]
	v_mfma_i32_16x16x64_i8 v[122:125], v[198:201], v[206:209], v[122:125]
	v_mfma_i32_16x16x64_i8 v[110:113], v[174:177], v[214:217], v[110:113]
	v_mfma_i32_16x16x64_i8 v[106:109], v[198:201], v[214:217], v[106:109]
	v_mfma_i32_16x16x64_i8 v[94:97], v[174:177], v[222:225], v[94:97]
	v_mfma_i32_16x16x64_i8 v[90:93], v[198:201], v[222:225], v[90:93]
	v_mfma_i32_16x16x64_i8 v[78:81], v[174:177], v[230:233], v[78:81]
	v_mfma_i32_16x16x64_i8 v[74:77], v[198:201], v[230:233], v[74:77]
	s_setprio 0
	s_barrier
	s_add_i32 s62, s65, s14
	v_lshl_add_u64 v[178:179], v[178:179], 0, s[36:37]
	s_mov_b32 m0, s62
	ds_read_b128 v[202:205], v193 offset:49152
	ds_read_b128 v[206:209], v193 offset:50176
	ds_read_b128 v[210:213], v193 offset:51200
	ds_read_b128 v[214:217], v193 offset:52224
	ds_read_b128 v[218:221], v193 offset:53248
	ds_read_b128 v[222:225], v193 offset:54272
	ds_read_b128 v[226:229], v193 offset:55296
	ds_read_b128 v[230:233], v193 offset:56320
	global_load_lds_dwordx4 v[178:179], off
	s_add_i32 m0, s62, 0x2000
	s_add_u32 s60, s60, 0x80080
	v_lshl_add_u64 v[178:179], v[182:183], 0, s[36:37]
	s_addc_u32 s61, s61, 0
	s_add_i32 s62, s66, s14
	global_load_lds_dwordx4 v[178:179], off
	v_lshl_add_u64 v[178:179], s[60:61], 0, v[150:151]
	s_mov_b32 m0, s62
	s_nop 0
	global_load_lds_dwordx4 v[178:179], off
	v_lshl_add_u64 v[178:179], s[60:61], 0, v[146:147]
	s_add_i32 m0, s62, 0x2000
	s_nop 0
	global_load_lds_dwordx4 v[178:179], off
	v_lshl_add_u64 v[178:179], v[186:187], 0, s[36:37]
	s_mov_b32 m0, s21
	s_nop 0
	global_load_lds_dwordx4 v[178:179], off
	v_lshl_add_u64 v[178:179], v[190:191], 0, s[36:37]
	s_mov_b32 m0, s22
	s_nop 0
	global_load_lds_dwordx4 v[178:179], off
	s_waitcnt vmcnt(8)
	s_waitcnt lgkmcnt(0)
	s_barrier
	s_setprio 1
	s_waitcnt lgkmcnt(0)
	v_mfma_i32_16x16x64_i8 v[70:73], v[58:61], v[202:205], v[70:73]
	v_mfma_i32_16x16x64_i8 v[66:69], v[138:141], v[202:205], v[66:69]
	v_mfma_i32_16x16x64_i8 v[46:49], v[58:61], v[210:213], v[46:49]
	v_mfma_i32_16x16x64_i8 v[42:45], v[138:141], v[210:213], v[42:45]
	v_mfma_i32_16x16x64_i8 v[30:33], v[58:61], v[218:221], v[30:33]
	v_mfma_i32_16x16x64_i8 v[26:29], v[138:141], v[218:221], v[26:29]
	v_mfma_i32_16x16x64_i8 v[14:17], v[58:61], v[226:229], v[14:17]
	v_mfma_i32_16x16x64_i8 v[10:13], v[138:141], v[226:229], v[10:13]
	v_mfma_i32_16x16x64_i8 v[70:73], v[62:65], v[206:209], v[70:73]
	v_mfma_i32_16x16x64_i8 v[66:69], v[142:145], v[206:209], v[66:69]
	v_mfma_i32_16x16x64_i8 v[46:49], v[62:65], v[214:217], v[46:49]
	v_mfma_i32_16x16x64_i8 v[42:45], v[142:145], v[214:217], v[42:45]
	v_mfma_i32_16x16x64_i8 v[30:33], v[62:65], v[222:225], v[30:33]
	v_mfma_i32_16x16x64_i8 v[26:29], v[142:145], v[222:225], v[26:29]
	v_mfma_i32_16x16x64_i8 v[14:17], v[62:65], v[230:233], v[14:17]
	v_mfma_i32_16x16x64_i8 v[10:13], v[142:145], v[230:233], v[10:13]
	v_mfma_i32_16x16x64_i8 v[50:53], v[168:171], v[202:205], v[50:53]
	v_mfma_i32_16x16x64_i8 v[62:65], v[174:177], v[206:209], v[50:53]
	v_mfma_i32_16x16x64_i8 v[50:53], v[194:197], v[202:205], v[54:57]
	v_mfma_i32_16x16x64_i8 v[38:41], v[168:171], v[210:213], v[38:41]
	v_mfma_i32_16x16x64_i8 v[34:37], v[194:197], v[210:213], v[34:37]
	v_mfma_i32_16x16x64_i8 v[22:25], v[168:171], v[218:221], v[22:25]
	v_mfma_i32_16x16x64_i8 v[18:21], v[194:197], v[218:221], v[18:21]
	v_mfma_i32_16x16x64_i8 v[6:9], v[168:171], v[226:229], v[6:9]
	v_mfma_i32_16x16x64_i8 v[2:5], v[194:197], v[226:229], v[2:5]
	v_mfma_i32_16x16x64_i8 v[58:61], v[198:201], v[206:209], v[50:53]
	v_mfma_i32_16x16x64_i8 v[38:41], v[174:177], v[214:217], v[38:41]
	v_mfma_i32_16x16x64_i8 v[34:37], v[198:201], v[214:217], v[34:37]
	v_mfma_i32_16x16x64_i8 v[22:25], v[174:177], v[222:225], v[22:25]
	v_mfma_i32_16x16x64_i8 v[18:21], v[198:201], v[222:225], v[18:21]
	v_mfma_i32_16x16x64_i8 v[6:9], v[174:177], v[230:233], v[6:9]
	v_mfma_i32_16x16x64_i8 v[2:5], v[198:201], v[230:233], v[2:5]
	s_setprio 0
	s_barrier
	s_add_i32 s64, s64, 2
	s_add_u32 s52, s52, 0x100
	s_addc_u32 s53, s53, 0
	s_add_u32 s43, s43, 0x100
	s_addc_u32 s51, s51, 0
	s_cmp_lt_u32 s64, 30
	s_cbranch_scc1 .LBB0_116
	s_nop 0
	s_nop 0
	s_nop 0
	s_nop 0
	s_nop 0
	s_nop 0
	s_nop 0
	s_nop 0
	s_andn2_b64 vcc, exec, s[38:39]
	s_cbranch_vccnz .LBB0_119
	s_barrier

.LBB0_256:
	ds_read_b128 v[126:129], v175
	ds_read_b128 v[130:133], v175 offset:1024
	ds_read_b128 v[138:141], v175 offset:2048
	ds_read_b128 v[142:145], v175 offset:3072
	ds_read_b128 v[164:167], v176
	ds_read_b128 v[168:171], v176 offset:1024
	ds_read_b128 v[178:181], v176 offset:2048
	ds_read_b128 v[182:185], v176 offset:3072
	s_add_u32 s48, s46, 0xffea8080
	s_addc_u32 s49, s47, -1
	s_cmpk_eq_i32 s52, 0x52
	s_cselect_b32 s51, s5, s49
	s_cselect_b32 s50, s4, s48
	s_cselect_b32 s49, s43, s35
	s_cselect_b32 s48, s42, s34
	v_lshl_add_u64 v[218:219], s[46:47], 0, v[156:157]
	s_add_i32 m0, s15, 0xc000
	ds_read_b128 v[186:189], v177
	ds_read_b128 v[190:193], v177 offset:1024
	ds_read_b128 v[194:197], v177 offset:2048
	ds_read_b128 v[198:201], v177 offset:3072
	ds_read_b128 v[202:205], v177 offset:4096
	ds_read_b128 v[206:209], v177 offset:5120
	ds_read_b128 v[210:213], v177 offset:6144
	ds_read_b128 v[214:217], v177 offset:7168
	global_load_lds_dwordx4 v[218:219], off
	v_lshl_add_u64 v[218:219], s[46:47], 0, v[158:159]
	s_add_i32 m0, s15, 0xe000
	s_nop 0
	global_load_lds_dwordx4 v[218:219], off
	s_waitcnt vmcnt(8)
	s_waitcnt lgkmcnt(0)
	s_barrier
	s_setprio 1
	s_waitcnt lgkmcnt(0)
	v_mfma_i32_16x16x64_i8 v[134:137], v[126:129], v[186:189], v[134:137]
	v_mfma_i32_16x16x64_i8 v[122:125], v[138:141], v[186:189], v[122:125]
	v_mfma_i32_16x16x64_i8 v[110:113], v[126:129], v[194:197], v[110:113]
	v_mfma_i32_16x16x64_i8 v[106:109], v[138:141], v[194:197], v[106:109]
	v_mfma_i32_16x16x64_i8 v[94:97], v[126:129], v[202:205], v[94:97]
	v_mfma_i32_16x16x64_i8 v[90:93], v[138:141], v[202:205], v[90:93]
	v_mfma_i32_16x16x64_i8 v[78:81], v[126:129], v[210:213], v[78:81]
	v_mfma_i32_16x16x64_i8 v[74:77], v[138:141], v[210:213], v[74:77]
	v_mfma_i32_16x16x64_i8 v[134:137], v[130:133], v[190:193], v[134:137]
	v_mfma_i32_16x16x64_i8 v[122:125], v[142:145], v[190:193], v[122:125]
	v_mfma_i32_16x16x64_i8 v[110:113], v[130:133], v[198:201], v[110:113]
	v_mfma_i32_16x16x64_i8 v[106:109], v[142:145], v[198:201], v[106:109]
	v_mfma_i32_16x16x64_i8 v[94:97], v[130:133], v[206:209], v[94:97]
	v_mfma_i32_16x16x64_i8 v[90:93], v[142:145], v[206:209], v[90:93]
	v_mfma_i32_16x16x64_i8 v[78:81], v[130:133], v[214:217], v[78:81]
	v_mfma_i32_16x16x64_i8 v[74:77], v[142:145], v[214:217], v[74:77]
	v_mfma_i32_16x16x64_i8 v[118:121], v[164:167], v[186:189], v[118:121]
	v_mfma_i32_16x16x64_i8 v[114:117], v[178:181], v[186:189], v[114:117]
	v_mfma_i32_16x16x64_i8 v[102:105], v[164:167], v[194:197], v[102:105]
	v_mfma_i32_16x16x64_i8 v[98:101], v[178:181], v[194:197], v[98:101]
	v_mfma_i32_16x16x64_i8 v[86:89], v[164:167], v[202:205], v[86:89]
	v_mfma_i32_16x16x64_i8 v[82:85], v[178:181], v[202:205], v[82:85]
	v_mfma_i32_16x16x64_i8 v[70:73], v[164:167], v[210:213], v[70:73]
	v_mfma_i32_16x16x64_i8 v[66:69], v[178:181], v[210:213], v[66:69]
	v_mfma_i32_16x16x64_i8 v[118:121], v[168:171], v[190:193], v[118:121]
	v_mfma_i32_16x16x64_i8 v[114:117], v[182:185], v[190:193], v[114:117]
	v_mfma_i32_16x16x64_i8 v[102:105], v[168:171], v[198:201], v[102:105]
	v_mfma_i32_16x16x64_i8 v[98:101], v[182:185], v[198:201], v[98:101]
	v_mfma_i32_16x16x64_i8 v[86:89], v[168:171], v[206:209], v[86:89]
	v_mfma_i32_16x16x64_i8 v[82:85], v[182:185], v[206:209], v[82:85]
	v_mfma_i32_16x16x64_i8 v[70:73], v[168:171], v[214:217], v[70:73]
	v_mfma_i32_16x16x64_i8 v[66:69], v[182:185], v[214:217], v[66:69]
	s_setprio 0
	s_barrier
	s_add_i32 s53, s23, s12
	v_lshl_add_u64 v[218:219], s[48:49], 0, v[150:151]
	s_mov_b32 m0, s53
	ds_read_b128 v[186:189], v177 offset:16384
	ds_read_b128 v[190:193], v177 offset:17408
	ds_read_b128 v[194:197], v177 offset:18432
	ds_read_b128 v[198:201], v177 offset:19456
	ds_read_b128 v[202:205], v177 offset:20480
	ds_read_b128 v[206:209], v177 offset:21504
	ds_read_b128 v[210:213], v177 offset:22528
	ds_read_b128 v[214:217], v177 offset:23552
	global_load_lds_dwordx4 v[218:219], off
	s_add_i32 m0, s53, 0x2000
	s_add_u32 s60, s48, 0x158000
	v_lshl_add_u64 v[220:221], s[48:49], 0, v[146:147]
	s_addc_u32 s61, s49, 0
	s_add_i32 s53, s24, s12
	global_load_lds_dwordx4 v[220:221], off
	v_lshl_add_u64 v[222:223], s[60:61], 0, v[150:151]
	s_mov_b32 m0, s53
	v_lshl_add_u64 v[224:225], s[50:51], 0, v[148:149]
	global_load_lds_dwordx4 v[222:223], off
	v_lshl_add_u64 v[222:223], s[60:61], 0, v[146:147]
	s_add_i32 m0, s53, 0x2000
	s_nop 0
	global_load_lds_dwordx4 v[222:223], off
	v_lshl_add_u64 v[222:223], s[50:51], 0, v[152:153]
	s_mov_b32 m0, s15
	s_nop 0
	global_load_lds_dwordx4 v[222:223], off
	s_mov_b32 m0, s16
	s_nop 0
	global_load_lds_dwordx4 v[224:225], off
	s_waitcnt vmcnt(8)
	s_waitcnt lgkmcnt(0)
	s_barrier
	s_setprio 1
	s_waitcnt lgkmcnt(0)
	v_mfma_i32_16x16x64_i8 v[62:65], v[126:129], v[186:189], v[62:65]
	v_mfma_i32_16x16x64_i8 v[58:61], v[138:141], v[186:189], v[58:61]
	v_mfma_i32_16x16x64_i8 v[46:49], v[126:129], v[194:197], v[46:49]
	v_mfma_i32_16x16x64_i8 v[42:45], v[138:141], v[194:197], v[42:45]
	v_mfma_i32_16x16x64_i8 v[30:33], v[126:129], v[202:205], v[30:33]
	v_mfma_i32_16x16x64_i8 v[26:29], v[138:141], v[202:205], v[26:29]
	v_mfma_i32_16x16x64_i8 v[14:17], v[126:129], v[210:213], v[14:17]
	v_mfma_i32_16x16x64_i8 v[10:13], v[138:141], v[210:213], v[10:13]
	v_mfma_i32_16x16x64_i8 v[62:65], v[130:133], v[190:193], v[62:65]
	v_mfma_i32_16x16x64_i8 v[58:61], v[142:145], v[190:193], v[58:61]
	v_mfma_i32_16x16x64_i8 v[46:49], v[130:133], v[198:201], v[46:49]
	v_mfma_i32_16x16x64_i8 v[42:45], v[142:145], v[198:201], v[42:45]
	v_mfma_i32_16x16x64_i8 v[30:33], v[130:133], v[206:209], v[30:33]
	v_mfma_i32_16x16x64_i8 v[26:29], v[142:145], v[206:209], v[26:29]
	v_mfma_i32_16x16x64_i8 v[14:17], v[130:133], v[214:217], v[14:17]
	v_mfma_i32_16x16x64_i8 v[10:13], v[142:145], v[214:217], v[10:13]
	v_mfma_i32_16x16x64_i8 v[54:57], v[164:167], v[186:189], v[54:57]
	v_mfma_i32_16x16x64_i8 v[50:53], v[178:181], v[186:189], v[50:53]
	v_mfma_i32_16x16x64_i8 v[38:41], v[164:167], v[194:197], v[38:41]
	v_mfma_i32_16x16x64_i8 v[34:37], v[178:181], v[194:197], v[34:37]
	v_mfma_i32_16x16x64_i8 v[22:25], v[164:167], v[202:205], v[22:25]
	v_mfma_i32_16x16x64_i8 v[18:21], v[178:181], v[202:205], v[18:21]
	v_mfma_i32_16x16x64_i8 v[6:9], v[164:167], v[210:213], v[6:9]
	v_mfma_i32_16x16x64_i8 v[2:5], v[178:181], v[210:213], v[2:5]
	v_mfma_i32_16x16x64_i8 v[54:57], v[168:171], v[190:193], v[54:57]
	v_mfma_i32_16x16x64_i8 v[50:53], v[182:185], v[190:193], v[50:53]
	v_mfma_i32_16x16x64_i8 v[38:41], v[168:171], v[198:201], v[38:41]
	v_mfma_i32_16x16x64_i8 v[34:37], v[182:185], v[198:201], v[34:37]
	v_mfma_i32_16x16x64_i8 v[22:25], v[168:171], v[206:209], v[22:25]
	v_mfma_i32_16x16x64_i8 v[18:21], v[182:185], v[206:209], v[18:21]
	v_mfma_i32_16x16x64_i8 v[6:9], v[168:171], v[214:217], v[6:9]
	v_mfma_i32_16x16x64_i8 v[2:5], v[182:185], v[214:217], v[2:5]
	s_setprio 0
	s_barrier
	s_add_i32 s53, 0, 0x18000
	s_add_i32 s60, 0, 0x1c000
	v_add_u32_e32 v142, s53, v173
	v_add_u32_e32 v154, s60, v173
	ds_read_b128 v[126:129], v142
	ds_read_b128 v[130:133], v142 offset:1024
	ds_read_b128 v[138:141], v142 offset:2048
	ds_read_b128 v[142:145], v142 offset:3072
	ds_read_b128 v[164:167], v154
	ds_read_b128 v[168:171], v154 offset:1024
	ds_read_b128 v[178:181], v154 offset:2048
	ds_read_b128 v[182:185], v154 offset:3072
	s_add_u32 s50, s50, 0x158000
	s_addc_u32 s51, s51, 0
	s_mov_b32 m0, s17
	v_lshl_add_u64 v[226:227], s[50:51], 0, v[152:153]
	ds_read_b128 v[186:189], v177 offset:32768
	ds_read_b128 v[190:193], v177 offset:33792
	ds_read_b128 v[194:197], v177 offset:34816
	ds_read_b128 v[198:201], v177 offset:35840
	ds_read_b128 v[202:205], v177 offset:36864
	ds_read_b128 v[206:209], v177 offset:37888
	ds_read_b128 v[210:213], v177 offset:38912
	ds_read_b128 v[214:217], v177 offset:39936
	global_load_lds_dwordx4 v[226:227], off
	v_lshl_add_u64 v[226:227], s[50:51], 0, v[148:149]
	s_mov_b32 m0, s18
	s_nop 0
	global_load_lds_dwordx4 v[226:227], off
	s_waitcnt vmcnt(8)
	s_waitcnt lgkmcnt(0)
	s_barrier
	s_setprio 1
	s_waitcnt lgkmcnt(0)
	v_mfma_i32_16x16x64_i8 v[134:137], v[126:129], v[186:189], v[134:137]
	v_mfma_i32_16x16x64_i8 v[122:125], v[138:141], v[186:189], v[122:125]
	v_mfma_i32_16x16x64_i8 v[110:113], v[126:129], v[194:197], v[110:113]
	v_mfma_i32_16x16x64_i8 v[106:109], v[138:141], v[194:197], v[106:109]
	v_mfma_i32_16x16x64_i8 v[94:97], v[126:129], v[202:205], v[94:97]
	v_mfma_i32_16x16x64_i8 v[90:93], v[138:141], v[202:205], v[90:93]
	v_mfma_i32_16x16x64_i8 v[78:81], v[126:129], v[210:213], v[78:81]
	v_mfma_i32_16x16x64_i8 v[74:77], v[138:141], v[210:213], v[74:77]
	v_mfma_i32_16x16x64_i8 v[134:137], v[130:133], v[190:193], v[134:137]
	v_mfma_i32_16x16x64_i8 v[122:125], v[142:145], v[190:193], v[122:125]
	v_mfma_i32_16x16x64_i8 v[110:113], v[130:133], v[198:201], v[110:113]
	v_mfma_i32_16x16x64_i8 v[106:109], v[142:145], v[198:201], v[106:109]
	v_mfma_i32_16x16x64_i8 v[94:97], v[130:133], v[206:209], v[94:97]
	v_mfma_i32_16x16x64_i8 v[90:93], v[142:145], v[206:209], v[90:93]
	v_mfma_i32_16x16x64_i8 v[78:81], v[130:133], v[214:217], v[78:81]
	v_mfma_i32_16x16x64_i8 v[74:77], v[142:145], v[214:217], v[74:77]
	v_mfma_i32_16x16x64_i8 v[118:121], v[164:167], v[186:189], v[118:121]
	v_mfma_i32_16x16x64_i8 v[114:117], v[178:181], v[186:189], v[114:117]
	v_mfma_i32_16x16x64_i8 v[102:105], v[164:167], v[194:197], v[102:105]
	v_mfma_i32_16x16x64_i8 v[98:101], v[178:181], v[194:197], v[98:101]
	v_mfma_i32_16x16x64_i8 v[86:89], v[164:167], v[202:205], v[86:89]
	v_mfma_i32_16x16x64_i8 v[82:85], v[178:181], v[202:205], v[82:85]
	v_mfma_i32_16x16x64_i8 v[70:73], v[164:167], v[210:213], v[70:73]
	v_mfma_i32_16x16x64_i8 v[66:69], v[178:181], v[210:213], v[66:69]
	v_mfma_i32_16x16x64_i8 v[118:121], v[168:171], v[190:193], v[118:121]
	v_mfma_i32_16x16x64_i8 v[114:117], v[182:185], v[190:193], v[114:117]
	v_mfma_i32_16x16x64_i8 v[102:105], v[168:171], v[198:201], v[102:105]
	v_mfma_i32_16x16x64_i8 v[98:101], v[182:185], v[198:201], v[98:101]
	v_mfma_i32_16x16x64_i8 v[86:89], v[168:171], v[206:209], v[86:89]
	v_mfma_i32_16x16x64_i8 v[82:85], v[182:185], v[206:209], v[82:85]
	v_mfma_i32_16x16x64_i8 v[70:73], v[168:171], v[214:217], v[70:73]
	v_mfma_i32_16x16x64_i8 v[66:69], v[182:185], v[214:217], v[66:69]
	s_setprio 0
	s_barrier
	s_add_i32 s50, s53, s12
	v_lshl_add_u64 v[218:219], v[218:219], 0, s[38:39]
	s_mov_b32 m0, s50
	ds_read_b128 v[186:189], v177 offset:49152
	ds_read_b128 v[190:193], v177 offset:50176
	ds_read_b128 v[194:197], v177 offset:51200
	ds_read_b128 v[198:201], v177 offset:52224
	ds_read_b128 v[202:205], v177 offset:53248
	ds_read_b128 v[206:209], v177 offset:54272
	ds_read_b128 v[210:213], v177 offset:55296
	ds_read_b128 v[214:217], v177 offset:56320
	global_load_lds_dwordx4 v[218:219], off
	s_add_i32 m0, s50, 0x2000
	s_add_u32 s48, s48, 0x158080
	v_lshl_add_u64 v[218:219], v[220:221], 0, s[38:39]
	s_addc_u32 s49, s49, 0
	s_add_i32 s50, s60, s12
	global_load_lds_dwordx4 v[218:219], off
	v_lshl_add_u64 v[218:219], s[48:49], 0, v[150:151]
	s_mov_b32 m0, s50
	s_nop 0
	global_load_lds_dwordx4 v[218:219], off
	v_lshl_add_u64 v[218:219], s[48:49], 0, v[146:147]
	s_add_i32 m0, s50, 0x2000
	s_nop 0
	global_load_lds_dwordx4 v[218:219], off
	v_lshl_add_u64 v[218:219], v[222:223], 0, s[38:39]
	s_mov_b32 m0, s20
	s_nop 0
	global_load_lds_dwordx4 v[218:219], off
	v_lshl_add_u64 v[218:219], v[224:225], 0, s[38:39]
	s_mov_b32 m0, s21
	s_nop 0
	global_load_lds_dwordx4 v[218:219], off
	s_waitcnt vmcnt(8)
	s_waitcnt lgkmcnt(0)
	s_barrier
	s_setprio 1
	s_waitcnt lgkmcnt(0)
	v_mfma_i32_16x16x64_i8 v[62:65], v[126:129], v[186:189], v[62:65]
	v_mfma_i32_16x16x64_i8 v[58:61], v[138:141], v[186:189], v[58:61]
	v_mfma_i32_16x16x64_i8 v[46:49], v[126:129], v[194:197], v[46:49]
	v_mfma_i32_16x16x64_i8 v[42:45], v[138:141], v[194:197], v[42:45]
	v_mfma_i32_16x16x64_i8 v[30:33], v[126:129], v[202:205], v[30:33]
	v_mfma_i32_16x16x64_i8 v[26:29], v[138:141], v[202:205], v[26:29]
	v_mfma_i32_16x16x64_i8 v[14:17], v[126:129], v[210:213], v[14:17]
	v_mfma_i32_16x16x64_i8 v[10:13], v[138:141], v[210:213], v[10:13]
	v_mfma_i32_16x16x64_i8 v[62:65], v[130:133], v[190:193], v[62:65]
	v_mfma_i32_16x16x64_i8 v[58:61], v[142:145], v[190:193], v[58:61]
	v_mfma_i32_16x16x64_i8 v[46:49], v[130:133], v[198:201], v[46:49]
	v_mfma_i32_16x16x64_i8 v[42:45], v[142:145], v[198:201], v[42:45]
	v_mfma_i32_16x16x64_i8 v[30:33], v[130:133], v[206:209], v[30:33]
	v_mfma_i32_16x16x64_i8 v[26:29], v[142:145], v[206:209], v[26:29]
	v_mfma_i32_16x16x64_i8 v[14:17], v[130:133], v[214:217], v[14:17]
	v_mfma_i32_16x16x64_i8 v[10:13], v[142:145], v[214:217], v[10:13]
	v_mfma_i32_16x16x64_i8 v[54:57], v[164:167], v[186:189], v[54:57]
	v_mfma_i32_16x16x64_i8 v[50:53], v[178:181], v[186:189], v[50:53]
	v_mfma_i32_16x16x64_i8 v[38:41], v[164:167], v[194:197], v[38:41]
	v_mfma_i32_16x16x64_i8 v[34:37], v[178:181], v[194:197], v[34:37]
	v_mfma_i32_16x16x64_i8 v[22:25], v[164:167], v[202:205], v[22:25]
	v_mfma_i32_16x16x64_i8 v[18:21], v[178:181], v[202:205], v[18:21]
	v_mfma_i32_16x16x64_i8 v[6:9], v[164:167], v[210:213], v[6:9]
	v_mfma_i32_16x16x64_i8 v[2:5], v[178:181], v[210:213], v[2:5]
	v_mfma_i32_16x16x64_i8 v[54:57], v[168:171], v[190:193], v[54:57]
	v_mfma_i32_16x16x64_i8 v[50:53], v[182:185], v[190:193], v[50:53]
	v_mfma_i32_16x16x64_i8 v[38:41], v[168:171], v[198:201], v[38:41]
	v_mfma_i32_16x16x64_i8 v[34:37], v[182:185], v[198:201], v[34:37]
	v_mfma_i32_16x16x64_i8 v[22:25], v[168:171], v[206:209], v[22:25]
	v_mfma_i32_16x16x64_i8 v[18:21], v[182:185], v[206:209], v[18:21]
	v_mfma_i32_16x16x64_i8 v[6:9], v[168:171], v[214:217], v[6:9]
	v_mfma_i32_16x16x64_i8 v[2:5], v[182:185], v[214:217], v[2:5]
	s_setprio 0
	s_barrier
	s_add_i32 s52, s52, 2
	s_add_u32 s46, s46, 0x100
	s_addc_u32 s47, s47, 0
	s_add_u32 s34, s34, 0x100
	s_addc_u32 s35, s35, 0
	s_cmpk_lt_u32 s52, 0x54
	s_cbranch_scc1 .LBB0_256
	s_nop 0
	s_nop 0
	s_nop 0
	s_nop 0
	s_nop 0
	s_nop 0
	s_nop 0
	s_nop 0
	s_andn2_b64 vcc, exec, s[40:41]
	s_cbranch_vccnz .LBB0_259
	s_barrier

.LBB0_429:
	ds_read_b128 v[74:77], v173
	ds_read_b128 v[78:81], v173 offset:1024
	ds_read_b128 v[90:93], v173 offset:2048
	ds_read_b128 v[94:97], v173 offset:3072
	ds_read_b128 v[164:167], v174
	ds_read_b128 v[176:179], v174 offset:1024
	ds_read_b128 v[180:183], v174 offset:2048
	ds_read_b128 v[184:187], v174 offset:3072
	s_add_u32 s50, s48, 0xfff80080
	s_addc_u32 s51, s49, -1
	s_cmp_eq_u32 s61, 28
	s_cselect_b32 s53, s39, s51
	s_cselect_b32 s52, s47, s50
	s_cselect_b32 s51, s37, s60
	s_cselect_b32 s50, s56, s57
	v_lshl_add_u64 v[168:169], s[48:49], 0, v[158:159]
	s_add_i32 m0, s19, 0xc000
	ds_read_b128 v[188:191], v175
	ds_read_b128 v[192:195], v175 offset:1024
	ds_read_b128 v[196:199], v175 offset:2048
	ds_read_b128 v[200:203], v175 offset:3072
	ds_read_b128 v[204:207], v175 offset:4096
	ds_read_b128 v[208:211], v175 offset:5120
	ds_read_b128 v[212:215], v175 offset:6144
	ds_read_b128 v[216:219], v175 offset:7168
	global_load_lds_dwordx4 v[168:169], off
	v_lshl_add_u64 v[168:169], s[48:49], 0, v[160:161]
	s_add_i32 m0, s19, 0xe000
	s_nop 0
	global_load_lds_dwordx4 v[168:169], off
	s_waitcnt vmcnt(8)
	s_waitcnt lgkmcnt(0)
	s_barrier
	s_setprio 1
	s_waitcnt lgkmcnt(0)
	v_mfma_i32_16x16x64_i8 v[142:145], v[74:77], v[188:191], v[142:145]
	v_mfma_i32_16x16x64_i8 v[138:141], v[90:93], v[188:191], v[138:141]
	v_mfma_i32_16x16x64_i8 v[126:129], v[74:77], v[196:199], v[126:129]
	v_mfma_i32_16x16x64_i8 v[122:125], v[90:93], v[196:199], v[122:125]
	v_mfma_i32_16x16x64_i8 v[110:113], v[74:77], v[204:207], v[110:113]
	v_mfma_i32_16x16x64_i8 v[106:109], v[90:93], v[204:207], v[106:109]
	v_mfma_i32_16x16x64_i8 v[86:89], v[74:77], v[212:215], v[86:89]
	v_mfma_i32_16x16x64_i8 v[82:85], v[90:93], v[212:215], v[82:85]
	v_mfma_i32_16x16x64_i8 v[142:145], v[78:81], v[192:195], v[142:145]
	v_mfma_i32_16x16x64_i8 v[138:141], v[94:97], v[192:195], v[138:141]
	v_mfma_i32_16x16x64_i8 v[126:129], v[78:81], v[200:203], v[126:129]
	v_mfma_i32_16x16x64_i8 v[122:125], v[94:97], v[200:203], v[122:125]
	v_mfma_i32_16x16x64_i8 v[110:113], v[78:81], v[208:211], v[110:113]
	v_mfma_i32_16x16x64_i8 v[106:109], v[94:97], v[208:211], v[106:109]
	v_mfma_i32_16x16x64_i8 v[86:89], v[78:81], v[216:219], v[86:89]
	v_mfma_i32_16x16x64_i8 v[82:85], v[94:97], v[216:219], v[82:85]
	v_mfma_i32_16x16x64_i8 v[134:137], v[164:167], v[188:191], v[134:137]
	v_mfma_i32_16x16x64_i8 v[130:133], v[180:183], v[188:191], v[130:133]
	v_mfma_i32_16x16x64_i8 v[118:121], v[164:167], v[196:199], v[118:121]
	v_mfma_i32_16x16x64_i8 v[114:117], v[180:183], v[196:199], v[114:117]
	v_mfma_i32_16x16x64_i8 v[102:105], v[164:167], v[204:207], v[102:105]
	v_mfma_i32_16x16x64_i8 v[98:101], v[180:183], v[204:207], v[98:101]
	v_mfma_i32_16x16x64_i8 v[70:73], v[164:167], v[212:215], v[70:73]
	v_mfma_i32_16x16x64_i8 v[66:69], v[180:183], v[212:215], v[66:69]
	v_mfma_i32_16x16x64_i8 v[134:137], v[176:179], v[192:195], v[134:137]
	v_mfma_i32_16x16x64_i8 v[130:133], v[184:187], v[192:195], v[130:133]
	v_mfma_i32_16x16x64_i8 v[118:121], v[176:179], v[200:203], v[118:121]
	v_mfma_i32_16x16x64_i8 v[114:117], v[184:187], v[200:203], v[114:117]
	v_mfma_i32_16x16x64_i8 v[102:105], v[176:179], v[208:211], v[102:105]
	v_mfma_i32_16x16x64_i8 v[98:101], v[184:187], v[208:211], v[98:101]
	v_mfma_i32_16x16x64_i8 v[70:73], v[176:179], v[216:219], v[70:73]
	v_mfma_i32_16x16x64_i8 v[66:69], v[184:187], v[216:219], v[66:69]
	s_setprio 0
	s_barrier
	s_add_i32 s62, s35, s13
	v_lshl_add_u64 v[168:169], s[50:51], 0, v[148:149]
	s_mov_b32 m0, s62
	ds_read_b128 v[188:191], v175 offset:16384
	ds_read_b128 v[192:195], v175 offset:17408
	ds_read_b128 v[196:199], v175 offset:18432
	ds_read_b128 v[200:203], v175 offset:19456
	ds_read_b128 v[204:207], v175 offset:20480
	ds_read_b128 v[208:211], v175 offset:21504
	ds_read_b128 v[212:215], v175 offset:22528
	ds_read_b128 v[216:219], v175 offset:23552
	global_load_lds_dwordx4 v[168:169], off
	s_add_i32 m0, s62, 0x2000
	s_add_u32 s62, s50, 0x80000
	v_lshl_add_u64 v[220:221], s[50:51], 0, v[152:153]
	s_addc_u32 s63, s51, 0
	s_add_i32 s64, s54, s13
	global_load_lds_dwordx4 v[220:221], off
	v_lshl_add_u64 v[222:223], s[62:63], 0, v[148:149]
	s_mov_b32 m0, s64
	v_lshl_add_u64 v[224:225], s[52:53], 0, v[150:151]
	global_load_lds_dwordx4 v[222:223], off
	v_lshl_add_u64 v[222:223], s[62:63], 0, v[152:153]
	s_add_i32 m0, s64, 0x2000
	s_nop 0
	global_load_lds_dwordx4 v[222:223], off
	v_lshl_add_u64 v[222:223], s[52:53], 0, v[146:147]
	s_mov_b32 m0, s19
	s_nop 0
	global_load_lds_dwordx4 v[222:223], off
	s_mov_b32 m0, s20
	s_nop 0
	global_load_lds_dwordx4 v[224:225], off
	s_waitcnt vmcnt(8)
	s_waitcnt lgkmcnt(0)
	s_barrier
	s_setprio 1
	s_waitcnt lgkmcnt(0)
	v_mfma_i32_16x16x64_i8 v[62:65], v[74:77], v[188:191], v[62:65]
	v_mfma_i32_16x16x64_i8 v[58:61], v[90:93], v[188:191], v[58:61]
	v_mfma_i32_16x16x64_i8 v[46:49], v[74:77], v[196:199], v[46:49]
	v_mfma_i32_16x16x64_i8 v[42:45], v[90:93], v[196:199], v[42:45]
	v_mfma_i32_16x16x64_i8 v[30:33], v[74:77], v[204:207], v[30:33]
	v_mfma_i32_16x16x64_i8 v[26:29], v[90:93], v[204:207], v[26:29]
	v_mfma_i32_16x16x64_i8 v[14:17], v[74:77], v[212:215], v[14:17]
	v_mfma_i32_16x16x64_i8 v[10:13], v[90:93], v[212:215], v[10:13]
	v_mfma_i32_16x16x64_i8 v[62:65], v[78:81], v[192:195], v[62:65]
	v_mfma_i32_16x16x64_i8 v[58:61], v[94:97], v[192:195], v[58:61]
	v_mfma_i32_16x16x64_i8 v[46:49], v[78:81], v[200:203], v[46:49]
	v_mfma_i32_16x16x64_i8 v[42:45], v[94:97], v[200:203], v[42:45]
	v_mfma_i32_16x16x64_i8 v[30:33], v[78:81], v[208:211], v[30:33]
	v_mfma_i32_16x16x64_i8 v[26:29], v[94:97], v[208:211], v[26:29]
	v_mfma_i32_16x16x64_i8 v[14:17], v[78:81], v[216:219], v[14:17]
	v_mfma_i32_16x16x64_i8 v[10:13], v[94:97], v[216:219], v[10:13]
	v_mfma_i32_16x16x64_i8 v[54:57], v[164:167], v[188:191], v[54:57]
	v_mfma_i32_16x16x64_i8 v[50:53], v[180:183], v[188:191], v[50:53]
	v_mfma_i32_16x16x64_i8 v[38:41], v[164:167], v[196:199], v[38:41]
	v_mfma_i32_16x16x64_i8 v[34:37], v[180:183], v[196:199], v[34:37]
	v_mfma_i32_16x16x64_i8 v[22:25], v[164:167], v[204:207], v[22:25]
	v_mfma_i32_16x16x64_i8 v[18:21], v[180:183], v[204:207], v[18:21]
	v_mfma_i32_16x16x64_i8 v[6:9], v[164:167], v[212:215], v[6:9]
	v_mfma_i32_16x16x64_i8 v[2:5], v[180:183], v[212:215], v[2:5]
	v_mfma_i32_16x16x64_i8 v[54:57], v[176:179], v[192:195], v[54:57]
	v_mfma_i32_16x16x64_i8 v[50:53], v[184:187], v[192:195], v[50:53]
	v_mfma_i32_16x16x64_i8 v[38:41], v[176:179], v[200:203], v[38:41]
	v_mfma_i32_16x16x64_i8 v[34:37], v[184:187], v[200:203], v[34:37]
	v_mfma_i32_16x16x64_i8 v[22:25], v[176:179], v[208:211], v[22:25]
	v_mfma_i32_16x16x64_i8 v[18:21], v[184:187], v[208:211], v[18:21]
	v_mfma_i32_16x16x64_i8 v[6:9], v[176:179], v[216:219], v[6:9]
	v_mfma_i32_16x16x64_i8 v[2:5], v[184:187], v[216:219], v[2:5]
	s_setprio 0
	s_barrier
	s_add_i32 s62, 0, 0x18000
	s_add_i32 s63, 0, 0x1c000
	v_add_u32_e32 v94, s62, v171
	v_add_u32_e32 v184, s63, v171
	ds_read_b128 v[74:77], v94
	ds_read_b128 v[78:81], v94 offset:1024
	ds_read_b128 v[90:93], v94 offset:2048
	ds_read_b128 v[94:97], v94 offset:3072
	ds_read_b128 v[164:167], v184
	ds_read_b128 v[176:179], v184 offset:1024
	ds_read_b128 v[180:183], v184 offset:2048
	ds_read_b128 v[184:187], v184 offset:3072
	s_add_u32 s52, s52, 0x80000
	s_addc_u32 s53, s53, 0
	s_mov_b32 m0, s21
	v_lshl_add_u64 v[226:227], s[52:53], 0, v[146:147]
	ds_read_b128 v[188:191], v175 offset:32768
	ds_read_b128 v[192:195], v175 offset:33792
	ds_read_b128 v[196:199], v175 offset:34816
	ds_read_b128 v[200:203], v175 offset:35840
	ds_read_b128 v[204:207], v175 offset:36864
	ds_read_b128 v[208:211], v175 offset:37888
	ds_read_b128 v[212:215], v175 offset:38912
	ds_read_b128 v[216:219], v175 offset:39936
	global_load_lds_dwordx4 v[226:227], off
	v_lshl_add_u64 v[226:227], s[52:53], 0, v[150:151]
	s_mov_b32 m0, s22
	s_nop 0
	global_load_lds_dwordx4 v[226:227], off
	s_waitcnt vmcnt(8)
	s_waitcnt lgkmcnt(0)
	s_barrier
	s_setprio 1
	s_waitcnt lgkmcnt(0)
	v_mfma_i32_16x16x64_i8 v[142:145], v[74:77], v[188:191], v[142:145]
	v_mfma_i32_16x16x64_i8 v[138:141], v[90:93], v[188:191], v[138:141]
	v_mfma_i32_16x16x64_i8 v[126:129], v[74:77], v[196:199], v[126:129]
	v_mfma_i32_16x16x64_i8 v[122:125], v[90:93], v[196:199], v[122:125]
	v_mfma_i32_16x16x64_i8 v[110:113], v[74:77], v[204:207], v[110:113]
	v_mfma_i32_16x16x64_i8 v[106:109], v[90:93], v[204:207], v[106:109]
	v_mfma_i32_16x16x64_i8 v[86:89], v[74:77], v[212:215], v[86:89]
	v_mfma_i32_16x16x64_i8 v[82:85], v[90:93], v[212:215], v[82:85]
	v_mfma_i32_16x16x64_i8 v[142:145], v[78:81], v[192:195], v[142:145]
	v_mfma_i32_16x16x64_i8 v[138:141], v[94:97], v[192:195], v[138:141]
	v_mfma_i32_16x16x64_i8 v[126:129], v[78:81], v[200:203], v[126:129]
	v_mfma_i32_16x16x64_i8 v[122:125], v[94:97], v[200:203], v[122:125]
	v_mfma_i32_16x16x64_i8 v[110:113], v[78:81], v[208:211], v[110:113]
	v_mfma_i32_16x16x64_i8 v[106:109], v[94:97], v[208:211], v[106:109]
	v_mfma_i32_16x16x64_i8 v[86:89], v[78:81], v[216:219], v[86:89]
	v_mfma_i32_16x16x64_i8 v[82:85], v[94:97], v[216:219], v[82:85]
	v_mfma_i32_16x16x64_i8 v[134:137], v[164:167], v[188:191], v[134:137]
	v_mfma_i32_16x16x64_i8 v[130:133], v[180:183], v[188:191], v[130:133]
	v_mfma_i32_16x16x64_i8 v[118:121], v[164:167], v[196:199], v[118:121]
	v_mfma_i32_16x16x64_i8 v[114:117], v[180:183], v[196:199], v[114:117]
	v_mfma_i32_16x16x64_i8 v[102:105], v[164:167], v[204:207], v[102:105]
	v_mfma_i32_16x16x64_i8 v[98:101], v[180:183], v[204:207], v[98:101]
	v_mfma_i32_16x16x64_i8 v[70:73], v[164:167], v[212:215], v[70:73]
	v_mfma_i32_16x16x64_i8 v[66:69], v[180:183], v[212:215], v[66:69]
	v_mfma_i32_16x16x64_i8 v[134:137], v[176:179], v[192:195], v[134:137]
	v_mfma_i32_16x16x64_i8 v[130:133], v[184:187], v[192:195], v[130:133]
	v_mfma_i32_16x16x64_i8 v[118:121], v[176:179], v[200:203], v[118:121]
	v_mfma_i32_16x16x64_i8 v[114:117], v[184:187], v[200:203], v[114:117]
	v_mfma_i32_16x16x64_i8 v[102:105], v[176:179], v[208:211], v[102:105]
	v_mfma_i32_16x16x64_i8 v[98:101], v[184:187], v[208:211], v[98:101]
	v_mfma_i32_16x16x64_i8 v[70:73], v[176:179], v[216:219], v[70:73]
	v_mfma_i32_16x16x64_i8 v[66:69], v[184:187], v[216:219], v[66:69]
	s_setprio 0
	s_barrier
	s_add_i32 s52, s62, s13
	v_lshl_add_u64 v[168:169], v[168:169], 0, s[8:9]
	s_mov_b32 m0, s52
	ds_read_b128 v[188:191], v175 offset:49152
	ds_read_b128 v[192:195], v175 offset:50176
	ds_read_b128 v[196:199], v175 offset:51200
	ds_read_b128 v[200:203], v175 offset:52224
	ds_read_b128 v[204:207], v175 offset:53248
	ds_read_b128 v[208:211], v175 offset:54272
	ds_read_b128 v[212:215], v175 offset:55296
	ds_read_b128 v[216:219], v175 offset:56320
	global_load_lds_dwordx4 v[168:169], off
	s_add_i32 m0, s52, 0x2000
	s_add_u32 s50, s50, 0x80080
	v_lshl_add_u64 v[168:169], v[220:221], 0, s[8:9]
	s_addc_u32 s51, s51, 0
	s_add_i32 s52, s63, s13
	global_load_lds_dwordx4 v[168:169], off
	v_lshl_add_u64 v[168:169], s[50:51], 0, v[148:149]
	s_mov_b32 m0, s52
	s_nop 0
	global_load_lds_dwordx4 v[168:169], off
	v_lshl_add_u64 v[168:169], s[50:51], 0, v[152:153]
	s_add_i32 m0, s52, 0x2000
	s_nop 0
	global_load_lds_dwordx4 v[168:169], off
	v_lshl_add_u64 v[168:169], v[222:223], 0, s[8:9]
	s_mov_b32 m0, s24
	s_nop 0
	global_load_lds_dwordx4 v[168:169], off
	v_lshl_add_u64 v[168:169], v[224:225], 0, s[8:9]
	s_mov_b32 m0, s25
	s_nop 0
	global_load_lds_dwordx4 v[168:169], off
	s_waitcnt vmcnt(8)
	s_waitcnt lgkmcnt(0)
	s_barrier
	s_setprio 1
	s_waitcnt lgkmcnt(0)
	v_mfma_i32_16x16x64_i8 v[62:65], v[74:77], v[188:191], v[62:65]
	v_mfma_i32_16x16x64_i8 v[58:61], v[90:93], v[188:191], v[58:61]
	v_mfma_i32_16x16x64_i8 v[46:49], v[74:77], v[196:199], v[46:49]
	v_mfma_i32_16x16x64_i8 v[42:45], v[90:93], v[196:199], v[42:45]
	v_mfma_i32_16x16x64_i8 v[30:33], v[74:77], v[204:207], v[30:33]
	v_mfma_i32_16x16x64_i8 v[26:29], v[90:93], v[204:207], v[26:29]
	v_mfma_i32_16x16x64_i8 v[14:17], v[74:77], v[212:215], v[14:17]
	v_mfma_i32_16x16x64_i8 v[10:13], v[90:93], v[212:215], v[10:13]
	v_mfma_i32_16x16x64_i8 v[62:65], v[78:81], v[192:195], v[62:65]
	v_mfma_i32_16x16x64_i8 v[58:61], v[94:97], v[192:195], v[58:61]
	v_mfma_i32_16x16x64_i8 v[46:49], v[78:81], v[200:203], v[46:49]
	v_mfma_i32_16x16x64_i8 v[42:45], v[94:97], v[200:203], v[42:45]
	v_mfma_i32_16x16x64_i8 v[30:33], v[78:81], v[208:211], v[30:33]
	v_mfma_i32_16x16x64_i8 v[26:29], v[94:97], v[208:211], v[26:29]
	v_mfma_i32_16x16x64_i8 v[14:17], v[78:81], v[216:219], v[14:17]
	v_mfma_i32_16x16x64_i8 v[10:13], v[94:97], v[216:219], v[10:13]
	v_mfma_i32_16x16x64_i8 v[54:57], v[164:167], v[188:191], v[54:57]
	v_mfma_i32_16x16x64_i8 v[50:53], v[180:183], v[188:191], v[50:53]
	v_mfma_i32_16x16x64_i8 v[38:41], v[164:167], v[196:199], v[38:41]
	v_mfma_i32_16x16x64_i8 v[34:37], v[180:183], v[196:199], v[34:37]
	v_mfma_i32_16x16x64_i8 v[22:25], v[164:167], v[204:207], v[22:25]
	v_mfma_i32_16x16x64_i8 v[18:21], v[180:183], v[204:207], v[18:21]
	v_mfma_i32_16x16x64_i8 v[6:9], v[164:167], v[212:215], v[6:9]
	v_mfma_i32_16x16x64_i8 v[2:5], v[180:183], v[212:215], v[2:5]
	v_mfma_i32_16x16x64_i8 v[54:57], v[176:179], v[192:195], v[54:57]
	v_mfma_i32_16x16x64_i8 v[50:53], v[184:187], v[192:195], v[50:53]
	v_mfma_i32_16x16x64_i8 v[38:41], v[176:179], v[200:203], v[38:41]
	v_mfma_i32_16x16x64_i8 v[34:37], v[184:187], v[200:203], v[34:37]
	v_mfma_i32_16x16x64_i8 v[22:25], v[176:179], v[208:211], v[22:25]
	v_mfma_i32_16x16x64_i8 v[18:21], v[184:187], v[208:211], v[18:21]
	v_mfma_i32_16x16x64_i8 v[6:9], v[176:179], v[216:219], v[6:9]
	v_mfma_i32_16x16x64_i8 v[2:5], v[184:187], v[216:219], v[2:5]
	s_setprio 0
	s_barrier
	s_add_i32 s61, s61, 2
	s_add_u32 s48, s48, 0x100
	s_addc_u32 s49, s49, 0
	s_add_u32 s57, s57, 0x100
	s_addc_u32 s60, s60, 0
	s_cmp_lt_u32 s61, 30
	s_cbranch_scc1 .LBB0_429
	s_nop 0
	s_nop 0
	s_nop 0
	s_nop 0
	s_nop 0
	s_nop 0
	s_nop 0
	s_nop 0
	s_andn2_b64 vcc, exec, s[10:11]
	s_cbranch_vccz .LBB0_434
	v_lshl_add_u32 v164, s46, 8, v170
	s_cmp_gt_i32 s55, 39
	s_mov_b64 s[46:47], -1
	s_cbranch_scc1 .LBB0_435

.LBB0_449:
	ds_read_b128 v[148:151], v155
	ds_read_b128 v[158:161], v155 offset:1024
	ds_read_b128 v[162:165], v155 offset:2048
	ds_read_b128 v[166:169], v155 offset:3072
	ds_read_b128 v[170:173], v156
	ds_read_b128 v[174:177], v156 offset:1024
	ds_read_b128 v[178:181], v156 offset:2048
	ds_read_b128 v[182:185], v156 offset:3072
	s_add_u32 s50, s48, 0xfff00080
	s_addc_u32 s51, s49, -1
	s_cmp_eq_u32 s57, 60
	s_cselect_b32 s53, s41, s51
	s_cselect_b32 s52, s47, s50
	s_cselect_b32 s51, s39, s56
	s_cselect_b32 s50, s54, s55
	v_lshl_add_u64 v[218:219], s[48:49], 0, v[140:141]
	s_add_i32 m0, s18, 0xc000
	ds_read_b128 v[186:189], v157
	ds_read_b128 v[190:193], v157 offset:1024
	ds_read_b128 v[194:197], v157 offset:2048
	ds_read_b128 v[198:201], v157 offset:3072
	ds_read_b128 v[202:205], v157 offset:4096
	ds_read_b128 v[206:209], v157 offset:5120
	ds_read_b128 v[210:213], v157 offset:6144
	ds_read_b128 v[214:217], v157 offset:7168
	global_load_lds_dwordx4 v[218:219], off
	v_lshl_add_u64 v[218:219], s[48:49], 0, v[142:143]
	s_add_i32 m0, s18, 0xe000
	s_nop 0
	global_load_lds_dwordx4 v[218:219], off
	s_waitcnt vmcnt(8)
	s_waitcnt lgkmcnt(0)
	s_barrier
	s_setprio 1
	s_waitcnt lgkmcnt(0)
	v_mfma_f32_16x16x32_bf16 v[126:129], v[148:151], v[186:189], v[126:129]
	v_mfma_f32_16x16x32_bf16 v[122:125], v[162:165], v[186:189], v[122:125]
	v_mfma_f32_16x16x32_bf16 v[118:121], v[148:151], v[194:197], v[118:121]
	v_mfma_f32_16x16x32_bf16 v[110:113], v[162:165], v[194:197], v[110:113]
	v_mfma_f32_16x16x32_bf16 v[102:105], v[148:151], v[202:205], v[102:105]
	v_mfma_f32_16x16x32_bf16 v[94:97], v[162:165], v[202:205], v[94:97]
	v_mfma_f32_16x16x32_bf16 v[86:89], v[148:151], v[210:213], v[86:89]
	v_mfma_f32_16x16x32_bf16 v[78:81], v[162:165], v[210:213], v[78:81]
	v_mfma_f32_16x16x32_bf16 v[126:129], v[158:161], v[190:193], v[126:129]
	v_mfma_f32_16x16x32_bf16 v[122:125], v[166:169], v[190:193], v[122:125]
	v_mfma_f32_16x16x32_bf16 v[118:121], v[158:161], v[198:201], v[118:121]
	v_mfma_f32_16x16x32_bf16 v[110:113], v[166:169], v[198:201], v[110:113]
	v_mfma_f32_16x16x32_bf16 v[102:105], v[158:161], v[206:209], v[102:105]
	v_mfma_f32_16x16x32_bf16 v[94:97], v[166:169], v[206:209], v[94:97]
	v_mfma_f32_16x16x32_bf16 v[86:89], v[158:161], v[214:217], v[86:89]
	v_mfma_f32_16x16x32_bf16 v[78:81], v[166:169], v[214:217], v[78:81]
	v_mfma_f32_16x16x32_bf16 v[114:117], v[170:173], v[186:189], v[114:117]
	v_mfma_f32_16x16x32_bf16 v[106:109], v[178:181], v[186:189], v[106:109]
	v_mfma_f32_16x16x32_bf16 v[98:101], v[170:173], v[194:197], v[98:101]
	v_mfma_f32_16x16x32_bf16 v[90:93], v[178:181], v[194:197], v[90:93]
	v_mfma_f32_16x16x32_bf16 v[82:85], v[170:173], v[202:205], v[82:85]
	v_mfma_f32_16x16x32_bf16 v[74:77], v[178:181], v[202:205], v[74:77]
	v_mfma_f32_16x16x32_bf16 v[70:73], v[170:173], v[210:213], v[70:73]
	v_mfma_f32_16x16x32_bf16 v[66:69], v[178:181], v[210:213], v[66:69]
	v_mfma_f32_16x16x32_bf16 v[114:117], v[174:177], v[190:193], v[114:117]
	v_mfma_f32_16x16x32_bf16 v[106:109], v[182:185], v[190:193], v[106:109]
	v_mfma_f32_16x16x32_bf16 v[98:101], v[174:177], v[198:201], v[98:101]
	v_mfma_f32_16x16x32_bf16 v[90:93], v[182:185], v[198:201], v[90:93]
	v_mfma_f32_16x16x32_bf16 v[82:85], v[174:177], v[206:209], v[82:85]
	v_mfma_f32_16x16x32_bf16 v[74:77], v[182:185], v[206:209], v[74:77]
	v_mfma_f32_16x16x32_bf16 v[70:73], v[174:177], v[214:217], v[70:73]
	v_mfma_f32_16x16x32_bf16 v[66:69], v[182:185], v[214:217], v[66:69]
	s_setprio 0
	s_barrier
	s_add_i32 s60, s33, s16
	v_lshl_add_u64 v[218:219], s[50:51], 0, v[134:135]
	s_mov_b32 m0, s60
	ds_read_b128 v[186:189], v157 offset:16384
	ds_read_b128 v[190:193], v157 offset:17408
	ds_read_b128 v[194:197], v157 offset:18432
	ds_read_b128 v[198:201], v157 offset:19456
	ds_read_b128 v[202:205], v157 offset:20480
	ds_read_b128 v[206:209], v157 offset:21504
	ds_read_b128 v[210:213], v157 offset:22528
	ds_read_b128 v[214:217], v157 offset:23552
	global_load_lds_dwordx4 v[218:219], off
	s_add_i32 m0, s60, 0x2000
	s_add_u32 s60, s50, 0x100000
	v_lshl_add_u64 v[220:221], s[50:51], 0, v[130:131]
	s_addc_u32 s61, s51, 0
	s_add_i32 s62, s34, s16
	global_load_lds_dwordx4 v[220:221], off
	v_lshl_add_u64 v[222:223], s[60:61], 0, v[134:135]
	s_mov_b32 m0, s62
	v_lshl_add_u64 v[224:225], s[52:53], 0, v[132:133]
	global_load_lds_dwordx4 v[222:223], off
	v_lshl_add_u64 v[222:223], s[60:61], 0, v[130:131]
	s_add_i32 m0, s62, 0x2000
	s_nop 0
	global_load_lds_dwordx4 v[222:223], off
	v_lshl_add_u64 v[222:223], s[52:53], 0, v[136:137]
	s_mov_b32 m0, s18
	s_nop 0
	global_load_lds_dwordx4 v[222:223], off
	s_mov_b32 m0, s19
	s_nop 0
	global_load_lds_dwordx4 v[224:225], off
	s_waitcnt vmcnt(8)
	s_waitcnt lgkmcnt(0)
	s_barrier
	s_setprio 1
	s_waitcnt lgkmcnt(0)
	v_mfma_f32_16x16x32_bf16 v[62:65], v[148:151], v[186:189], v[62:65]
	v_mfma_f32_16x16x32_bf16 v[58:61], v[162:165], v[186:189], v[58:61]
	v_mfma_f32_16x16x32_bf16 v[54:57], v[148:151], v[194:197], v[54:57]
	v_mfma_f32_16x16x32_bf16 v[46:49], v[162:165], v[194:197], v[46:49]
	v_mfma_f32_16x16x32_bf16 v[38:41], v[148:151], v[202:205], v[38:41]
	v_mfma_f32_16x16x32_bf16 v[30:33], v[162:165], v[202:205], v[30:33]
	v_mfma_f32_16x16x32_bf16 v[22:25], v[148:151], v[210:213], v[22:25]
	v_mfma_f32_16x16x32_bf16 v[14:17], v[162:165], v[210:213], v[14:17]
	v_mfma_f32_16x16x32_bf16 v[62:65], v[158:161], v[190:193], v[62:65]
	v_mfma_f32_16x16x32_bf16 v[58:61], v[166:169], v[190:193], v[58:61]
	v_mfma_f32_16x16x32_bf16 v[54:57], v[158:161], v[198:201], v[54:57]
	v_mfma_f32_16x16x32_bf16 v[46:49], v[166:169], v[198:201], v[46:49]
	v_mfma_f32_16x16x32_bf16 v[38:41], v[158:161], v[206:209], v[38:41]
	v_mfma_f32_16x16x32_bf16 v[30:33], v[166:169], v[206:209], v[30:33]
	v_mfma_f32_16x16x32_bf16 v[22:25], v[158:161], v[214:217], v[22:25]
	v_mfma_f32_16x16x32_bf16 v[14:17], v[166:169], v[214:217], v[14:17]
	v_mfma_f32_16x16x32_bf16 v[50:53], v[170:173], v[186:189], v[50:53]
	v_mfma_f32_16x16x32_bf16 v[42:45], v[178:181], v[186:189], v[42:45]
	v_mfma_f32_16x16x32_bf16 v[34:37], v[170:173], v[194:197], v[34:37]
	v_mfma_f32_16x16x32_bf16 v[26:29], v[178:181], v[194:197], v[26:29]
	v_mfma_f32_16x16x32_bf16 v[18:21], v[170:173], v[202:205], v[18:21]
	v_mfma_f32_16x16x32_bf16 v[10:13], v[178:181], v[202:205], v[10:13]
	v_mfma_f32_16x16x32_bf16 v[6:9], v[170:173], v[210:213], v[6:9]
	v_mfma_f32_16x16x32_bf16 v[2:5], v[178:181], v[210:213], v[2:5]
	v_mfma_f32_16x16x32_bf16 v[50:53], v[174:177], v[190:193], v[50:53]
	v_mfma_f32_16x16x32_bf16 v[42:45], v[182:185], v[190:193], v[42:45]
	v_mfma_f32_16x16x32_bf16 v[34:37], v[174:177], v[198:201], v[34:37]
	v_mfma_f32_16x16x32_bf16 v[26:29], v[182:185], v[198:201], v[26:29]
	v_mfma_f32_16x16x32_bf16 v[18:21], v[174:177], v[206:209], v[18:21]
	v_mfma_f32_16x16x32_bf16 v[10:13], v[182:185], v[206:209], v[10:13]
	v_mfma_f32_16x16x32_bf16 v[6:9], v[174:177], v[214:217], v[6:9]
	v_mfma_f32_16x16x32_bf16 v[2:5], v[182:185], v[214:217], v[2:5]
	s_setprio 0
	s_barrier
	s_add_i32 s60, 0, 0x18000
	s_add_i32 s61, 0, 0x1c000
	v_add_u32_e32 v166, s60, v153
	v_add_u32_e32 v182, s61, v153
	ds_read_b128 v[148:151], v166
	ds_read_b128 v[158:161], v166 offset:1024
	ds_read_b128 v[162:165], v166 offset:2048
	ds_read_b128 v[166:169], v166 offset:3072
	ds_read_b128 v[170:173], v182
	ds_read_b128 v[174:177], v182 offset:1024
	ds_read_b128 v[178:181], v182 offset:2048
	ds_read_b128 v[182:185], v182 offset:3072
	s_add_u32 s52, s52, 0x100000
	s_addc_u32 s53, s53, 0
	s_mov_b32 m0, s20
	v_lshl_add_u64 v[226:227], s[52:53], 0, v[136:137]
	ds_read_b128 v[186:189], v157 offset:32768
	ds_read_b128 v[190:193], v157 offset:33792
	ds_read_b128 v[194:197], v157 offset:34816
	ds_read_b128 v[198:201], v157 offset:35840
	ds_read_b128 v[202:205], v157 offset:36864
	ds_read_b128 v[206:209], v157 offset:37888
	ds_read_b128 v[210:213], v157 offset:38912
	ds_read_b128 v[214:217], v157 offset:39936
	global_load_lds_dwordx4 v[226:227], off
	v_lshl_add_u64 v[226:227], s[52:53], 0, v[132:133]
	s_mov_b32 m0, s21
	s_nop 0
	global_load_lds_dwordx4 v[226:227], off
	s_waitcnt vmcnt(8)
	s_waitcnt lgkmcnt(0)
	s_barrier
	s_setprio 1
	s_waitcnt lgkmcnt(0)
	v_mfma_f32_16x16x32_bf16 v[126:129], v[148:151], v[186:189], v[126:129]
	v_mfma_f32_16x16x32_bf16 v[122:125], v[162:165], v[186:189], v[122:125]
	v_mfma_f32_16x16x32_bf16 v[118:121], v[148:151], v[194:197], v[118:121]
	v_mfma_f32_16x16x32_bf16 v[110:113], v[162:165], v[194:197], v[110:113]
	v_mfma_f32_16x16x32_bf16 v[102:105], v[148:151], v[202:205], v[102:105]
	v_mfma_f32_16x16x32_bf16 v[94:97], v[162:165], v[202:205], v[94:97]
	v_mfma_f32_16x16x32_bf16 v[86:89], v[148:151], v[210:213], v[86:89]
	v_mfma_f32_16x16x32_bf16 v[78:81], v[162:165], v[210:213], v[78:81]
	v_mfma_f32_16x16x32_bf16 v[126:129], v[158:161], v[190:193], v[126:129]
	v_mfma_f32_16x16x32_bf16 v[122:125], v[166:169], v[190:193], v[122:125]
	v_mfma_f32_16x16x32_bf16 v[118:121], v[158:161], v[198:201], v[118:121]
	v_mfma_f32_16x16x32_bf16 v[110:113], v[166:169], v[198:201], v[110:113]
	v_mfma_f32_16x16x32_bf16 v[102:105], v[158:161], v[206:209], v[102:105]
	v_mfma_f32_16x16x32_bf16 v[94:97], v[166:169], v[206:209], v[94:97]
	v_mfma_f32_16x16x32_bf16 v[86:89], v[158:161], v[214:217], v[86:89]
	v_mfma_f32_16x16x32_bf16 v[78:81], v[166:169], v[214:217], v[78:81]
	v_mfma_f32_16x16x32_bf16 v[114:117], v[170:173], v[186:189], v[114:117]
	v_mfma_f32_16x16x32_bf16 v[106:109], v[178:181], v[186:189], v[106:109]
	v_mfma_f32_16x16x32_bf16 v[98:101], v[170:173], v[194:197], v[98:101]
	v_mfma_f32_16x16x32_bf16 v[90:93], v[178:181], v[194:197], v[90:93]
	v_mfma_f32_16x16x32_bf16 v[82:85], v[170:173], v[202:205], v[82:85]
	v_mfma_f32_16x16x32_bf16 v[74:77], v[178:181], v[202:205], v[74:77]
	v_mfma_f32_16x16x32_bf16 v[70:73], v[170:173], v[210:213], v[70:73]
	v_mfma_f32_16x16x32_bf16 v[66:69], v[178:181], v[210:213], v[66:69]
	v_mfma_f32_16x16x32_bf16 v[114:117], v[174:177], v[190:193], v[114:117]
	v_mfma_f32_16x16x32_bf16 v[106:109], v[182:185], v[190:193], v[106:109]
	v_mfma_f32_16x16x32_bf16 v[98:101], v[174:177], v[198:201], v[98:101]
	v_mfma_f32_16x16x32_bf16 v[90:93], v[182:185], v[198:201], v[90:93]
	v_mfma_f32_16x16x32_bf16 v[82:85], v[174:177], v[206:209], v[82:85]
	v_mfma_f32_16x16x32_bf16 v[74:77], v[182:185], v[206:209], v[74:77]
	v_mfma_f32_16x16x32_bf16 v[70:73], v[174:177], v[214:217], v[70:73]
	v_mfma_f32_16x16x32_bf16 v[66:69], v[182:185], v[214:217], v[66:69]
	s_setprio 0
	s_barrier
	s_add_i32 s52, s60, s16
	v_lshl_add_u64 v[218:219], v[218:219], 0, s[28:29]
	s_mov_b32 m0, s52
	ds_read_b128 v[186:189], v157 offset:49152
	ds_read_b128 v[190:193], v157 offset:50176
	ds_read_b128 v[194:197], v157 offset:51200
	ds_read_b128 v[198:201], v157 offset:52224
	ds_read_b128 v[202:205], v157 offset:53248
	ds_read_b128 v[206:209], v157 offset:54272
	ds_read_b128 v[210:213], v157 offset:55296
	ds_read_b128 v[214:217], v157 offset:56320
	global_load_lds_dwordx4 v[218:219], off
	s_add_i32 m0, s52, 0x2000
	s_add_u32 s50, s50, 0x100080
	v_lshl_add_u64 v[218:219], v[220:221], 0, s[28:29]
	s_addc_u32 s51, s51, 0
	s_add_i32 s52, s61, s16
	global_load_lds_dwordx4 v[218:219], off
	v_lshl_add_u64 v[218:219], s[50:51], 0, v[134:135]
	s_mov_b32 m0, s52
	s_nop 0
	global_load_lds_dwordx4 v[218:219], off
	v_lshl_add_u64 v[218:219], s[50:51], 0, v[130:131]
	s_add_i32 m0, s52, 0x2000
	s_nop 0
	global_load_lds_dwordx4 v[218:219], off
	v_lshl_add_u64 v[218:219], v[222:223], 0, s[28:29]
	s_mov_b32 m0, s23
	s_nop 0
	global_load_lds_dwordx4 v[218:219], off
	v_lshl_add_u64 v[218:219], v[224:225], 0, s[28:29]
	s_mov_b32 m0, s24
	s_nop 0
	global_load_lds_dwordx4 v[218:219], off
	s_waitcnt vmcnt(8)
	s_waitcnt lgkmcnt(0)
	s_barrier
	s_setprio 1
	s_waitcnt lgkmcnt(0)
	v_mfma_f32_16x16x32_bf16 v[62:65], v[148:151], v[186:189], v[62:65]
	v_mfma_f32_16x16x32_bf16 v[58:61], v[162:165], v[186:189], v[58:61]
	v_mfma_f32_16x16x32_bf16 v[54:57], v[148:151], v[194:197], v[54:57]
	v_mfma_f32_16x16x32_bf16 v[46:49], v[162:165], v[194:197], v[46:49]
	v_mfma_f32_16x16x32_bf16 v[38:41], v[148:151], v[202:205], v[38:41]
	v_mfma_f32_16x16x32_bf16 v[30:33], v[162:165], v[202:205], v[30:33]
	v_mfma_f32_16x16x32_bf16 v[22:25], v[148:151], v[210:213], v[22:25]
	v_mfma_f32_16x16x32_bf16 v[14:17], v[162:165], v[210:213], v[14:17]
	v_mfma_f32_16x16x32_bf16 v[62:65], v[158:161], v[190:193], v[62:65]
	v_mfma_f32_16x16x32_bf16 v[58:61], v[166:169], v[190:193], v[58:61]
	v_mfma_f32_16x16x32_bf16 v[54:57], v[158:161], v[198:201], v[54:57]
	v_mfma_f32_16x16x32_bf16 v[46:49], v[166:169], v[198:201], v[46:49]
	v_mfma_f32_16x16x32_bf16 v[38:41], v[158:161], v[206:209], v[38:41]
	v_mfma_f32_16x16x32_bf16 v[30:33], v[166:169], v[206:209], v[30:33]
	v_mfma_f32_16x16x32_bf16 v[22:25], v[158:161], v[214:217], v[22:25]
	v_mfma_f32_16x16x32_bf16 v[14:17], v[166:169], v[214:217], v[14:17]
	v_mfma_f32_16x16x32_bf16 v[50:53], v[170:173], v[186:189], v[50:53]
	v_mfma_f32_16x16x32_bf16 v[42:45], v[178:181], v[186:189], v[42:45]
	v_mfma_f32_16x16x32_bf16 v[34:37], v[170:173], v[194:197], v[34:37]
	v_mfma_f32_16x16x32_bf16 v[26:29], v[178:181], v[194:197], v[26:29]
	v_mfma_f32_16x16x32_bf16 v[18:21], v[170:173], v[202:205], v[18:21]
	v_mfma_f32_16x16x32_bf16 v[10:13], v[178:181], v[202:205], v[10:13]
	v_mfma_f32_16x16x32_bf16 v[6:9], v[170:173], v[210:213], v[6:9]
	v_mfma_f32_16x16x32_bf16 v[2:5], v[178:181], v[210:213], v[2:5]
	v_mfma_f32_16x16x32_bf16 v[50:53], v[174:177], v[190:193], v[50:53]
	v_mfma_f32_16x16x32_bf16 v[42:45], v[182:185], v[190:193], v[42:45]
	v_mfma_f32_16x16x32_bf16 v[34:37], v[174:177], v[198:201], v[34:37]
	v_mfma_f32_16x16x32_bf16 v[26:29], v[182:185], v[198:201], v[26:29]
	v_mfma_f32_16x16x32_bf16 v[18:21], v[174:177], v[206:209], v[18:21]
	v_mfma_f32_16x16x32_bf16 v[10:13], v[182:185], v[206:209], v[10:13]
	v_mfma_f32_16x16x32_bf16 v[6:9], v[174:177], v[214:217], v[6:9]
	v_mfma_f32_16x16x32_bf16 v[2:5], v[182:185], v[214:217], v[2:5]
	s_setprio 0
	s_barrier
	s_add_i32 s57, s57, 2
	s_add_u32 s48, s48, 0x100
	s_addc_u32 s49, s49, 0
	s_add_u32 s55, s55, 0x100
	s_addc_u32 s56, s56, 0
	s_cmp_lt_u32 s57, 62
	s_cbranch_scc1 .LBB0_449
	s_nop 0
	s_nop 0
	s_nop 0
	s_nop 0
	s_nop 0
	s_nop 0
	s_nop 0
	s_nop 0
	s_andn2_b64 vcc, exec, s[30:31]
	s_cbranch_vccz .LBB0_454
	v_lshl_add_u32 v148, s46, 8, v152
	s_cmp_gt_i32 s35, 63
	s_mov_b64 s[46:47], -1
	s_cbranch_scc1 .LBB0_455

.LBB0_1007:
	ds_read_b128 v[122:125], v161
	ds_read_b128 v[126:129], v161 offset:1024
	ds_read_b128 v[138:141], v161 offset:2048
	ds_read_b128 v[164:167], v161 offset:3072
	ds_read_b128 v[168:171], v162
	ds_read_b128 v[172:175], v162 offset:1024
	ds_read_b128 v[176:179], v162 offset:2048
	ds_read_b128 v[180:183], v162 offset:3072
	s_add_u32 s26, s24, 0xfff00080
	s_addc_u32 s27, s25, -1
	s_cmp_eq_u32 s50, 60
	s_cselect_b32 s29, s17, s27
	s_cselect_b32 s28, s46, s26
	s_cselect_b32 s27, s15, s49
	s_cselect_b32 s26, s47, s48
	v_lshl_add_u64 v[216:217], s[24:25], 0, v[150:151]
	s_add_i32 m0, s34, 0xc000
	ds_read_b128 v[184:187], v163
	ds_read_b128 v[188:191], v163 offset:1024
	ds_read_b128 v[192:195], v163 offset:2048
	ds_read_b128 v[196:199], v163 offset:3072
	ds_read_b128 v[200:203], v163 offset:4096
	ds_read_b128 v[204:207], v163 offset:5120
	ds_read_b128 v[208:211], v163 offset:6144
	ds_read_b128 v[212:215], v163 offset:7168
	global_load_lds_dwordx4 v[216:217], off
	v_lshl_add_u64 v[216:217], s[24:25], 0, v[152:153]
	s_add_i32 m0, s34, 0xe000
	s_nop 0
	global_load_lds_dwordx4 v[216:217], off
	s_waitcnt vmcnt(8)
	s_waitcnt lgkmcnt(0)
	s_barrier
	s_setprio 1
	s_waitcnt lgkmcnt(0)
	v_mfma_f32_16x16x32_bf16 v[134:137], v[122:125], v[184:187], v[134:137]
	v_mfma_f32_16x16x32_bf16 v[130:133], v[138:141], v[184:187], v[130:133]
	v_mfma_f32_16x16x32_bf16 v[110:113], v[122:125], v[192:195], v[110:113]
	v_mfma_f32_16x16x32_bf16 v[106:109], v[138:141], v[192:195], v[106:109]
	v_mfma_f32_16x16x32_bf16 v[94:97], v[122:125], v[200:203], v[94:97]
	v_mfma_f32_16x16x32_bf16 v[90:93], v[138:141], v[200:203], v[90:93]
	v_mfma_f32_16x16x32_bf16 v[78:81], v[122:125], v[208:211], v[78:81]
	v_mfma_f32_16x16x32_bf16 v[74:77], v[138:141], v[208:211], v[74:77]
	v_mfma_f32_16x16x32_bf16 v[134:137], v[126:129], v[188:191], v[134:137]
	v_mfma_f32_16x16x32_bf16 v[130:133], v[164:167], v[188:191], v[130:133]
	v_mfma_f32_16x16x32_bf16 v[110:113], v[126:129], v[196:199], v[110:113]
	v_mfma_f32_16x16x32_bf16 v[106:109], v[164:167], v[196:199], v[106:109]
	v_mfma_f32_16x16x32_bf16 v[94:97], v[126:129], v[204:207], v[94:97]
	v_mfma_f32_16x16x32_bf16 v[90:93], v[164:167], v[204:207], v[90:93]
	v_mfma_f32_16x16x32_bf16 v[78:81], v[126:129], v[212:215], v[78:81]
	v_mfma_f32_16x16x32_bf16 v[74:77], v[164:167], v[212:215], v[74:77]
	v_mfma_f32_16x16x32_bf16 v[118:121], v[168:171], v[184:187], v[118:121]
	v_mfma_f32_16x16x32_bf16 v[114:117], v[176:179], v[184:187], v[114:117]
	v_mfma_f32_16x16x32_bf16 v[102:105], v[168:171], v[192:195], v[102:105]
	v_mfma_f32_16x16x32_bf16 v[98:101], v[176:179], v[192:195], v[98:101]
	v_mfma_f32_16x16x32_bf16 v[86:89], v[168:171], v[200:203], v[86:89]
	v_mfma_f32_16x16x32_bf16 v[82:85], v[176:179], v[200:203], v[82:85]
	v_mfma_f32_16x16x32_bf16 v[70:73], v[168:171], v[208:211], v[70:73]
	v_mfma_f32_16x16x32_bf16 v[66:69], v[176:179], v[208:211], v[66:69]
	v_mfma_f32_16x16x32_bf16 v[118:121], v[172:175], v[188:191], v[118:121]
	v_mfma_f32_16x16x32_bf16 v[114:117], v[180:183], v[188:191], v[114:117]
	v_mfma_f32_16x16x32_bf16 v[102:105], v[172:175], v[196:199], v[102:105]
	v_mfma_f32_16x16x32_bf16 v[98:101], v[180:183], v[196:199], v[98:101]
	v_mfma_f32_16x16x32_bf16 v[86:89], v[172:175], v[204:207], v[86:89]
	v_mfma_f32_16x16x32_bf16 v[82:85], v[180:183], v[204:207], v[82:85]
	v_mfma_f32_16x16x32_bf16 v[70:73], v[172:175], v[212:215], v[70:73]
	v_mfma_f32_16x16x32_bf16 v[66:69], v[180:183], v[212:215], v[66:69]
	s_setprio 0
	s_barrier
	s_add_i32 s51, s44, s33
	v_lshl_add_u64 v[216:217], s[26:27], 0, v[146:147]
	s_mov_b32 m0, s51
	ds_read_b128 v[184:187], v163 offset:16384
	ds_read_b128 v[188:191], v163 offset:17408
	ds_read_b128 v[192:195], v163 offset:18432
	ds_read_b128 v[196:199], v163 offset:19456
	ds_read_b128 v[200:203], v163 offset:20480
	ds_read_b128 v[204:207], v163 offset:21504
	ds_read_b128 v[208:211], v163 offset:22528
	ds_read_b128 v[212:215], v163 offset:23552
	global_load_lds_dwordx4 v[216:217], off
	s_add_i32 m0, s51, 0x2000
	s_add_u32 s52, s26, 0x100000
	v_lshl_add_u64 v[218:219], s[26:27], 0, v[142:143]
	s_addc_u32 s53, s27, 0
	s_add_i32 s51, s45, s33
	global_load_lds_dwordx4 v[218:219], off
	v_lshl_add_u64 v[220:221], s[52:53], 0, v[146:147]
	s_mov_b32 m0, s51
	v_lshl_add_u64 v[222:223], s[28:29], 0, v[144:145]
	global_load_lds_dwordx4 v[220:221], off
	v_lshl_add_u64 v[220:221], s[52:53], 0, v[142:143]
	s_add_i32 m0, s51, 0x2000
	s_nop 0
	global_load_lds_dwordx4 v[220:221], off
	v_lshl_add_u64 v[220:221], s[28:29], 0, v[148:149]
	s_mov_b32 m0, s34
	s_nop 0
	global_load_lds_dwordx4 v[220:221], off
	s_mov_b32 m0, s35
	s_nop 0
	global_load_lds_dwordx4 v[222:223], off
	s_waitcnt vmcnt(8)
	s_waitcnt lgkmcnt(0)
	s_barrier
	s_setprio 1
	s_waitcnt lgkmcnt(0)
	v_mfma_f32_16x16x32_bf16 v[62:65], v[122:125], v[184:187], v[62:65]
	v_mfma_f32_16x16x32_bf16 v[58:61], v[138:141], v[184:187], v[58:61]
	v_mfma_f32_16x16x32_bf16 v[46:49], v[122:125], v[192:195], v[46:49]
	v_mfma_f32_16x16x32_bf16 v[42:45], v[138:141], v[192:195], v[42:45]
	v_mfma_f32_16x16x32_bf16 v[30:33], v[122:125], v[200:203], v[30:33]
	v_mfma_f32_16x16x32_bf16 v[26:29], v[138:141], v[200:203], v[26:29]
	v_mfma_f32_16x16x32_bf16 v[14:17], v[122:125], v[208:211], v[14:17]
	v_mfma_f32_16x16x32_bf16 v[10:13], v[138:141], v[208:211], v[10:13]
	v_mfma_f32_16x16x32_bf16 v[62:65], v[126:129], v[188:191], v[62:65]
	v_mfma_f32_16x16x32_bf16 v[58:61], v[164:167], v[188:191], v[58:61]
	v_mfma_f32_16x16x32_bf16 v[46:49], v[126:129], v[196:199], v[46:49]
	v_mfma_f32_16x16x32_bf16 v[42:45], v[164:167], v[196:199], v[42:45]
	v_mfma_f32_16x16x32_bf16 v[30:33], v[126:129], v[204:207], v[30:33]
	v_mfma_f32_16x16x32_bf16 v[26:29], v[164:167], v[204:207], v[26:29]
	v_mfma_f32_16x16x32_bf16 v[14:17], v[126:129], v[212:215], v[14:17]
	v_mfma_f32_16x16x32_bf16 v[10:13], v[164:167], v[212:215], v[10:13]
	v_mfma_f32_16x16x32_bf16 v[54:57], v[168:171], v[184:187], v[54:57]
	v_mfma_f32_16x16x32_bf16 v[50:53], v[176:179], v[184:187], v[50:53]
	v_mfma_f32_16x16x32_bf16 v[38:41], v[168:171], v[192:195], v[38:41]
	v_mfma_f32_16x16x32_bf16 v[34:37], v[176:179], v[192:195], v[34:37]
	v_mfma_f32_16x16x32_bf16 v[22:25], v[168:171], v[200:203], v[22:25]
	v_mfma_f32_16x16x32_bf16 v[18:21], v[176:179], v[200:203], v[18:21]
	v_mfma_f32_16x16x32_bf16 v[6:9], v[168:171], v[208:211], v[6:9]
	v_mfma_f32_16x16x32_bf16 v[2:5], v[176:179], v[208:211], v[2:5]
	v_mfma_f32_16x16x32_bf16 v[54:57], v[172:175], v[188:191], v[54:57]
	v_mfma_f32_16x16x32_bf16 v[50:53], v[180:183], v[188:191], v[50:53]
	v_mfma_f32_16x16x32_bf16 v[38:41], v[172:175], v[196:199], v[38:41]
	v_mfma_f32_16x16x32_bf16 v[34:37], v[180:183], v[196:199], v[34:37]
	v_mfma_f32_16x16x32_bf16 v[22:25], v[172:175], v[204:207], v[22:25]
	v_mfma_f32_16x16x32_bf16 v[18:21], v[180:183], v[204:207], v[18:21]
	v_mfma_f32_16x16x32_bf16 v[6:9], v[172:175], v[212:215], v[6:9]
	v_mfma_f32_16x16x32_bf16 v[2:5], v[180:183], v[212:215], v[2:5]
	s_setprio 0
	s_barrier
	s_add_i32 s51, 0, 0x18000
	s_add_i32 s52, 0, 0x1c000
	v_add_u32_e32 v164, s51, v159
	v_add_u32_e32 v180, s52, v159
	ds_read_b128 v[122:125], v164
	ds_read_b128 v[126:129], v164 offset:1024
	ds_read_b128 v[138:141], v164 offset:2048
	ds_read_b128 v[164:167], v164 offset:3072
	ds_read_b128 v[168:171], v180
	ds_read_b128 v[172:175], v180 offset:1024
	ds_read_b128 v[176:179], v180 offset:2048
	ds_read_b128 v[180:183], v180 offset:3072
	s_add_u32 s28, s28, 0x100000
	s_addc_u32 s29, s29, 0
	s_mov_b32 m0, s36
	v_lshl_add_u64 v[224:225], s[28:29], 0, v[148:149]
	ds_read_b128 v[184:187], v163 offset:32768
	ds_read_b128 v[188:191], v163 offset:33792
	ds_read_b128 v[192:195], v163 offset:34816
	ds_read_b128 v[196:199], v163 offset:35840
	ds_read_b128 v[200:203], v163 offset:36864
	ds_read_b128 v[204:207], v163 offset:37888
	ds_read_b128 v[208:211], v163 offset:38912
	ds_read_b128 v[212:215], v163 offset:39936
	global_load_lds_dwordx4 v[224:225], off
	v_lshl_add_u64 v[224:225], s[28:29], 0, v[144:145]
	s_mov_b32 m0, s37
	s_nop 0
	global_load_lds_dwordx4 v[224:225], off
	s_waitcnt vmcnt(8)
	s_waitcnt lgkmcnt(0)
	s_barrier
	s_setprio 1
	s_waitcnt lgkmcnt(0)
	v_mfma_f32_16x16x32_bf16 v[134:137], v[122:125], v[184:187], v[134:137]
	v_mfma_f32_16x16x32_bf16 v[130:133], v[138:141], v[184:187], v[130:133]
	v_mfma_f32_16x16x32_bf16 v[110:113], v[122:125], v[192:195], v[110:113]
	v_mfma_f32_16x16x32_bf16 v[106:109], v[138:141], v[192:195], v[106:109]
	v_mfma_f32_16x16x32_bf16 v[94:97], v[122:125], v[200:203], v[94:97]
	v_mfma_f32_16x16x32_bf16 v[90:93], v[138:141], v[200:203], v[90:93]
	v_mfma_f32_16x16x32_bf16 v[78:81], v[122:125], v[208:211], v[78:81]
	v_mfma_f32_16x16x32_bf16 v[74:77], v[138:141], v[208:211], v[74:77]
	v_mfma_f32_16x16x32_bf16 v[134:137], v[126:129], v[188:191], v[134:137]
	v_mfma_f32_16x16x32_bf16 v[130:133], v[164:167], v[188:191], v[130:133]
	v_mfma_f32_16x16x32_bf16 v[110:113], v[126:129], v[196:199], v[110:113]
	v_mfma_f32_16x16x32_bf16 v[106:109], v[164:167], v[196:199], v[106:109]
	v_mfma_f32_16x16x32_bf16 v[94:97], v[126:129], v[204:207], v[94:97]
	v_mfma_f32_16x16x32_bf16 v[90:93], v[164:167], v[204:207], v[90:93]
	v_mfma_f32_16x16x32_bf16 v[78:81], v[126:129], v[212:215], v[78:81]
	v_mfma_f32_16x16x32_bf16 v[74:77], v[164:167], v[212:215], v[74:77]
	v_mfma_f32_16x16x32_bf16 v[118:121], v[168:171], v[184:187], v[118:121]
	v_mfma_f32_16x16x32_bf16 v[114:117], v[176:179], v[184:187], v[114:117]
	v_mfma_f32_16x16x32_bf16 v[102:105], v[168:171], v[192:195], v[102:105]
	v_mfma_f32_16x16x32_bf16 v[98:101], v[176:179], v[192:195], v[98:101]
	v_mfma_f32_16x16x32_bf16 v[86:89], v[168:171], v[200:203], v[86:89]
	v_mfma_f32_16x16x32_bf16 v[82:85], v[176:179], v[200:203], v[82:85]
	v_mfma_f32_16x16x32_bf16 v[70:73], v[168:171], v[208:211], v[70:73]
	v_mfma_f32_16x16x32_bf16 v[66:69], v[176:179], v[208:211], v[66:69]
	v_mfma_f32_16x16x32_bf16 v[118:121], v[172:175], v[188:191], v[118:121]
	v_mfma_f32_16x16x32_bf16 v[114:117], v[180:183], v[188:191], v[114:117]
	v_mfma_f32_16x16x32_bf16 v[102:105], v[172:175], v[196:199], v[102:105]
	v_mfma_f32_16x16x32_bf16 v[98:101], v[180:183], v[196:199], v[98:101]
	v_mfma_f32_16x16x32_bf16 v[86:89], v[172:175], v[204:207], v[86:89]
	v_mfma_f32_16x16x32_bf16 v[82:85], v[180:183], v[204:207], v[82:85]
	v_mfma_f32_16x16x32_bf16 v[70:73], v[172:175], v[212:215], v[70:73]
	v_mfma_f32_16x16x32_bf16 v[66:69], v[180:183], v[212:215], v[66:69]
	s_setprio 0
	s_barrier
	s_add_i32 s28, s51, s33
	v_lshl_add_u64 v[216:217], v[216:217], 0, s[10:11]
	s_mov_b32 m0, s28
	ds_read_b128 v[184:187], v163 offset:49152
	ds_read_b128 v[188:191], v163 offset:50176
	ds_read_b128 v[192:195], v163 offset:51200
	ds_read_b128 v[196:199], v163 offset:52224
	ds_read_b128 v[200:203], v163 offset:53248
	ds_read_b128 v[204:207], v163 offset:54272
	ds_read_b128 v[208:211], v163 offset:55296
	ds_read_b128 v[212:215], v163 offset:56320
	global_load_lds_dwordx4 v[216:217], off
	s_add_i32 m0, s28, 0x2000
	s_add_u32 s26, s26, 0x100080
	v_lshl_add_u64 v[216:217], v[218:219], 0, s[10:11]
	s_addc_u32 s27, s27, 0
	s_add_i32 s28, s52, s33
	global_load_lds_dwordx4 v[216:217], off
	v_lshl_add_u64 v[216:217], s[26:27], 0, v[146:147]
	s_mov_b32 m0, s28
	s_nop 0
	global_load_lds_dwordx4 v[216:217], off
	v_lshl_add_u64 v[216:217], s[26:27], 0, v[142:143]
	s_add_i32 m0, s28, 0x2000
	s_nop 0
	global_load_lds_dwordx4 v[216:217], off
	v_lshl_add_u64 v[216:217], v[220:221], 0, s[10:11]
	s_mov_b32 m0, s41
	s_nop 0
	global_load_lds_dwordx4 v[216:217], off
	v_lshl_add_u64 v[216:217], v[222:223], 0, s[10:11]
	s_mov_b32 m0, s42
	s_nop 0
	global_load_lds_dwordx4 v[216:217], off
	s_waitcnt vmcnt(8)
	s_waitcnt lgkmcnt(0)
	s_barrier
	s_setprio 1
	s_waitcnt lgkmcnt(0)
	v_mfma_f32_16x16x32_bf16 v[62:65], v[122:125], v[184:187], v[62:65]
	v_mfma_f32_16x16x32_bf16 v[58:61], v[138:141], v[184:187], v[58:61]
	v_mfma_f32_16x16x32_bf16 v[46:49], v[122:125], v[192:195], v[46:49]
	v_mfma_f32_16x16x32_bf16 v[42:45], v[138:141], v[192:195], v[42:45]
	v_mfma_f32_16x16x32_bf16 v[30:33], v[122:125], v[200:203], v[30:33]
	v_mfma_f32_16x16x32_bf16 v[26:29], v[138:141], v[200:203], v[26:29]
	v_mfma_f32_16x16x32_bf16 v[14:17], v[122:125], v[208:211], v[14:17]
	v_mfma_f32_16x16x32_bf16 v[10:13], v[138:141], v[208:211], v[10:13]
	v_mfma_f32_16x16x32_bf16 v[62:65], v[126:129], v[188:191], v[62:65]
	v_mfma_f32_16x16x32_bf16 v[58:61], v[164:167], v[188:191], v[58:61]
	v_mfma_f32_16x16x32_bf16 v[46:49], v[126:129], v[196:199], v[46:49]
	v_mfma_f32_16x16x32_bf16 v[42:45], v[164:167], v[196:199], v[42:45]
	v_mfma_f32_16x16x32_bf16 v[30:33], v[126:129], v[204:207], v[30:33]
	v_mfma_f32_16x16x32_bf16 v[26:29], v[164:167], v[204:207], v[26:29]
	v_mfma_f32_16x16x32_bf16 v[14:17], v[126:129], v[212:215], v[14:17]
	v_mfma_f32_16x16x32_bf16 v[10:13], v[164:167], v[212:215], v[10:13]
	v_mfma_f32_16x16x32_bf16 v[54:57], v[168:171], v[184:187], v[54:57]
	v_mfma_f32_16x16x32_bf16 v[50:53], v[176:179], v[184:187], v[50:53]
	v_mfma_f32_16x16x32_bf16 v[38:41], v[168:171], v[192:195], v[38:41]
	v_mfma_f32_16x16x32_bf16 v[34:37], v[176:179], v[192:195], v[34:37]
	v_mfma_f32_16x16x32_bf16 v[22:25], v[168:171], v[200:203], v[22:25]
	v_mfma_f32_16x16x32_bf16 v[18:21], v[176:179], v[200:203], v[18:21]
	v_mfma_f32_16x16x32_bf16 v[6:9], v[168:171], v[208:211], v[6:9]
	v_mfma_f32_16x16x32_bf16 v[2:5], v[176:179], v[208:211], v[2:5]
	v_mfma_f32_16x16x32_bf16 v[54:57], v[172:175], v[188:191], v[54:57]
	v_mfma_f32_16x16x32_bf16 v[50:53], v[180:183], v[188:191], v[50:53]
	v_mfma_f32_16x16x32_bf16 v[38:41], v[172:175], v[196:199], v[38:41]
	v_mfma_f32_16x16x32_bf16 v[34:37], v[180:183], v[196:199], v[34:37]
	v_mfma_f32_16x16x32_bf16 v[22:25], v[172:175], v[204:207], v[22:25]
	v_mfma_f32_16x16x32_bf16 v[18:21], v[180:183], v[204:207], v[18:21]
	v_mfma_f32_16x16x32_bf16 v[6:9], v[172:175], v[212:215], v[6:9]
	v_mfma_f32_16x16x32_bf16 v[2:5], v[180:183], v[212:215], v[2:5]
	s_setprio 0
	s_barrier
	s_add_i32 s50, s50, 2
	s_add_u32 s24, s24, 0x100
	s_addc_u32 s25, s25, 0
	s_add_u32 s48, s48, 0x100
	s_addc_u32 s49, s49, 0
	s_cmp_lt_u32 s50, 62
	s_cbranch_scc1 .LBB0_1007
	s_nop 0
	s_nop 0
	s_nop 0
	s_nop 0
	s_nop 0
	s_nop 0
	s_nop 0
	s_nop 0
	s_andn2_b64 vcc, exec, s[12:13]
	s_cbranch_vccnz .LBB0_1010
	s_barrier

.LBB0_1103:
	ds_read_b128 v[152:155], v148
	ds_read_b128 v[156:159], v148 offset:1024
	ds_read_b128 v[160:163], v148 offset:2048
	ds_read_b128 v[164:167], v148 offset:3072
	ds_read_b128 v[168:171], v149
	ds_read_b128 v[172:175], v149 offset:1024
	ds_read_b128 v[176:179], v149 offset:2048
	ds_read_b128 v[180:183], v149 offset:3072
	s_add_u32 s24, s22, 0xfff00080
	s_addc_u32 s25, s23, -1
	s_cmp_eq_u32 s48, 60
	s_cselect_b32 s27, s15, s25
	s_cselect_b32 s26, s44, s24
	s_cselect_b32 s25, s13, s47
	s_cselect_b32 s24, s45, s46
	v_lshl_add_u64 v[216:217], s[22:23], 0, v[138:139]
	s_add_i32 m0, s31, 0xc000
	ds_read_b128 v[184:187], v150
	ds_read_b128 v[188:191], v150 offset:1024
	ds_read_b128 v[192:195], v150 offset:2048
	ds_read_b128 v[196:199], v150 offset:3072
	ds_read_b128 v[200:203], v150 offset:4096
	ds_read_b128 v[204:207], v150 offset:5120
	ds_read_b128 v[208:211], v150 offset:6144
	ds_read_b128 v[212:215], v150 offset:7168
	global_load_lds_dwordx4 v[216:217], off
	v_lshl_add_u64 v[216:217], s[22:23], 0, v[140:141]
	s_add_i32 m0, s31, 0xe000
	s_nop 0
	global_load_lds_dwordx4 v[216:217], off
	s_waitcnt vmcnt(8)
	s_waitcnt lgkmcnt(0)
	s_barrier
	s_setprio 1
	s_waitcnt lgkmcnt(0)
	v_mfma_f32_16x16x32_bf16 v[126:129], v[152:155], v[184:187], v[126:129]
	v_mfma_f32_16x16x32_bf16 v[122:125], v[160:163], v[184:187], v[122:125]
	v_mfma_f32_16x16x32_bf16 v[110:113], v[152:155], v[192:195], v[110:113]
	v_mfma_f32_16x16x32_bf16 v[106:109], v[160:163], v[192:195], v[106:109]
	v_mfma_f32_16x16x32_bf16 v[94:97], v[152:155], v[200:203], v[94:97]
	v_mfma_f32_16x16x32_bf16 v[90:93], v[160:163], v[200:203], v[90:93]
	v_mfma_f32_16x16x32_bf16 v[78:81], v[152:155], v[208:211], v[78:81]
	v_mfma_f32_16x16x32_bf16 v[74:77], v[160:163], v[208:211], v[74:77]
	v_mfma_f32_16x16x32_bf16 v[126:129], v[156:159], v[188:191], v[126:129]
	v_mfma_f32_16x16x32_bf16 v[122:125], v[164:167], v[188:191], v[122:125]
	v_mfma_f32_16x16x32_bf16 v[110:113], v[156:159], v[196:199], v[110:113]
	v_mfma_f32_16x16x32_bf16 v[106:109], v[164:167], v[196:199], v[106:109]
	v_mfma_f32_16x16x32_bf16 v[94:97], v[156:159], v[204:207], v[94:97]
	v_mfma_f32_16x16x32_bf16 v[90:93], v[164:167], v[204:207], v[90:93]
	v_mfma_f32_16x16x32_bf16 v[78:81], v[156:159], v[212:215], v[78:81]
	v_mfma_f32_16x16x32_bf16 v[74:77], v[164:167], v[212:215], v[74:77]
	v_mfma_f32_16x16x32_bf16 v[118:121], v[168:171], v[184:187], v[118:121]
	v_mfma_f32_16x16x32_bf16 v[114:117], v[176:179], v[184:187], v[114:117]
	v_mfma_f32_16x16x32_bf16 v[102:105], v[168:171], v[192:195], v[102:105]
	v_mfma_f32_16x16x32_bf16 v[98:101], v[176:179], v[192:195], v[98:101]
	v_mfma_f32_16x16x32_bf16 v[86:89], v[168:171], v[200:203], v[86:89]
	v_mfma_f32_16x16x32_bf16 v[82:85], v[176:179], v[200:203], v[82:85]
	v_mfma_f32_16x16x32_bf16 v[70:73], v[168:171], v[208:211], v[70:73]
	v_mfma_f32_16x16x32_bf16 v[66:69], v[176:179], v[208:211], v[66:69]
	v_mfma_f32_16x16x32_bf16 v[118:121], v[172:175], v[188:191], v[118:121]
	v_mfma_f32_16x16x32_bf16 v[114:117], v[180:183], v[188:191], v[114:117]
	v_mfma_f32_16x16x32_bf16 v[102:105], v[172:175], v[196:199], v[102:105]
	v_mfma_f32_16x16x32_bf16 v[98:101], v[180:183], v[196:199], v[98:101]
	v_mfma_f32_16x16x32_bf16 v[86:89], v[172:175], v[204:207], v[86:89]
	v_mfma_f32_16x16x32_bf16 v[82:85], v[180:183], v[204:207], v[82:85]
	v_mfma_f32_16x16x32_bf16 v[70:73], v[172:175], v[212:215], v[70:73]
	v_mfma_f32_16x16x32_bf16 v[66:69], v[180:183], v[212:215], v[66:69]
	s_setprio 0
	s_barrier
	s_add_i32 s49, s42, s30
	v_lshl_add_u64 v[216:217], s[24:25], 0, v[134:135]
	s_mov_b32 m0, s49
	ds_read_b128 v[184:187], v150 offset:16384
	ds_read_b128 v[188:191], v150 offset:17408
	ds_read_b128 v[192:195], v150 offset:18432
	ds_read_b128 v[196:199], v150 offset:19456
	ds_read_b128 v[200:203], v150 offset:20480
	ds_read_b128 v[204:207], v150 offset:21504
	ds_read_b128 v[208:211], v150 offset:22528
	ds_read_b128 v[212:215], v150 offset:23552
	global_load_lds_dwordx4 v[216:217], off
	s_add_i32 m0, s49, 0x2000
	s_add_u32 s50, s24, 0x100000
	v_lshl_add_u64 v[218:219], s[24:25], 0, v[130:131]
	s_addc_u32 s51, s25, 0
	s_add_i32 s49, s43, s30
	global_load_lds_dwordx4 v[218:219], off
	v_lshl_add_u64 v[220:221], s[50:51], 0, v[134:135]
	s_mov_b32 m0, s49
	v_lshl_add_u64 v[222:223], s[26:27], 0, v[132:133]
	global_load_lds_dwordx4 v[220:221], off
	v_lshl_add_u64 v[220:221], s[50:51], 0, v[130:131]
	s_add_i32 m0, s49, 0x2000
	s_nop 0
	global_load_lds_dwordx4 v[220:221], off
	v_lshl_add_u64 v[220:221], s[26:27], 0, v[136:137]
	s_mov_b32 m0, s31
	s_nop 0
	global_load_lds_dwordx4 v[220:221], off
	s_mov_b32 m0, s33
	s_nop 0
	global_load_lds_dwordx4 v[222:223], off
	s_waitcnt vmcnt(8)
	s_waitcnt lgkmcnt(0)
	s_barrier
	s_setprio 1
	s_waitcnt lgkmcnt(0)
	v_mfma_f32_16x16x32_bf16 v[62:65], v[152:155], v[184:187], v[62:65]
	v_mfma_f32_16x16x32_bf16 v[58:61], v[160:163], v[184:187], v[58:61]
	v_mfma_f32_16x16x32_bf16 v[46:49], v[152:155], v[192:195], v[46:49]
	v_mfma_f32_16x16x32_bf16 v[42:45], v[160:163], v[192:195], v[42:45]
	v_mfma_f32_16x16x32_bf16 v[30:33], v[152:155], v[200:203], v[30:33]
	v_mfma_f32_16x16x32_bf16 v[26:29], v[160:163], v[200:203], v[26:29]
	v_mfma_f32_16x16x32_bf16 v[22:25], v[152:155], v[208:211], v[22:25]
	v_mfma_f32_16x16x32_bf16 v[18:21], v[160:163], v[208:211], v[18:21]
	v_mfma_f32_16x16x32_bf16 v[62:65], v[156:159], v[188:191], v[62:65]
	v_mfma_f32_16x16x32_bf16 v[58:61], v[164:167], v[188:191], v[58:61]
	v_mfma_f32_16x16x32_bf16 v[46:49], v[156:159], v[196:199], v[46:49]
	v_mfma_f32_16x16x32_bf16 v[42:45], v[164:167], v[196:199], v[42:45]
	v_mfma_f32_16x16x32_bf16 v[30:33], v[156:159], v[204:207], v[30:33]
	v_mfma_f32_16x16x32_bf16 v[26:29], v[164:167], v[204:207], v[26:29]
	v_mfma_f32_16x16x32_bf16 v[22:25], v[156:159], v[212:215], v[22:25]
	v_mfma_f32_16x16x32_bf16 v[18:21], v[164:167], v[212:215], v[18:21]
	v_mfma_f32_16x16x32_bf16 v[54:57], v[168:171], v[184:187], v[54:57]
	v_mfma_f32_16x16x32_bf16 v[50:53], v[176:179], v[184:187], v[50:53]
	v_mfma_f32_16x16x32_bf16 v[38:41], v[168:171], v[192:195], v[38:41]
	v_mfma_f32_16x16x32_bf16 v[34:37], v[176:179], v[192:195], v[34:37]
	v_mfma_f32_16x16x32_bf16 v[14:17], v[168:171], v[200:203], v[14:17]
	v_mfma_f32_16x16x32_bf16 v[10:13], v[176:179], v[200:203], v[10:13]
	v_mfma_f32_16x16x32_bf16 v[6:9], v[168:171], v[208:211], v[6:9]
	v_mfma_f32_16x16x32_bf16 v[2:5], v[176:179], v[208:211], v[2:5]
	v_mfma_f32_16x16x32_bf16 v[54:57], v[172:175], v[188:191], v[54:57]
	v_mfma_f32_16x16x32_bf16 v[50:53], v[180:183], v[188:191], v[50:53]
	v_mfma_f32_16x16x32_bf16 v[38:41], v[172:175], v[196:199], v[38:41]
	v_mfma_f32_16x16x32_bf16 v[34:37], v[180:183], v[196:199], v[34:37]
	v_mfma_f32_16x16x32_bf16 v[14:17], v[172:175], v[204:207], v[14:17]
	v_mfma_f32_16x16x32_bf16 v[10:13], v[180:183], v[204:207], v[10:13]
	v_mfma_f32_16x16x32_bf16 v[6:9], v[172:175], v[212:215], v[6:9]
	v_mfma_f32_16x16x32_bf16 v[2:5], v[180:183], v[212:215], v[2:5]
	s_setprio 0
	s_barrier
	s_add_i32 s49, 0, 0x18000
	s_add_i32 s50, 0, 0x1c000
	v_add_u32_e32 v164, s49, v147
	v_add_u32_e32 v180, s50, v147
	ds_read_b128 v[152:155], v164
	ds_read_b128 v[156:159], v164 offset:1024
	ds_read_b128 v[160:163], v164 offset:2048
	ds_read_b128 v[164:167], v164 offset:3072
	ds_read_b128 v[168:171], v180
	ds_read_b128 v[172:175], v180 offset:1024
	ds_read_b128 v[176:179], v180 offset:2048
	ds_read_b128 v[180:183], v180 offset:3072
	s_add_u32 s26, s26, 0x100000
	s_addc_u32 s27, s27, 0
	s_mov_b32 m0, s34
	v_lshl_add_u64 v[224:225], s[26:27], 0, v[136:137]
	ds_read_b128 v[184:187], v150 offset:32768
	ds_read_b128 v[188:191], v150 offset:33792
	ds_read_b128 v[192:195], v150 offset:34816
	ds_read_b128 v[196:199], v150 offset:35840
	ds_read_b128 v[200:203], v150 offset:36864
	ds_read_b128 v[204:207], v150 offset:37888
	ds_read_b128 v[208:211], v150 offset:38912
	ds_read_b128 v[212:215], v150 offset:39936
	global_load_lds_dwordx4 v[224:225], off
	v_lshl_add_u64 v[224:225], s[26:27], 0, v[132:133]
	s_mov_b32 m0, s35
	s_nop 0
	global_load_lds_dwordx4 v[224:225], off
	s_waitcnt vmcnt(8)
	s_waitcnt lgkmcnt(0)
	s_barrier
	s_setprio 1
	s_waitcnt lgkmcnt(0)
	v_mfma_f32_16x16x32_bf16 v[126:129], v[152:155], v[184:187], v[126:129]
	v_mfma_f32_16x16x32_bf16 v[122:125], v[160:163], v[184:187], v[122:125]
	v_mfma_f32_16x16x32_bf16 v[110:113], v[152:155], v[192:195], v[110:113]
	v_mfma_f32_16x16x32_bf16 v[106:109], v[160:163], v[192:195], v[106:109]
	v_mfma_f32_16x16x32_bf16 v[94:97], v[152:155], v[200:203], v[94:97]
	v_mfma_f32_16x16x32_bf16 v[90:93], v[160:163], v[200:203], v[90:93]
	v_mfma_f32_16x16x32_bf16 v[78:81], v[152:155], v[208:211], v[78:81]
	v_mfma_f32_16x16x32_bf16 v[74:77], v[160:163], v[208:211], v[74:77]
	v_mfma_f32_16x16x32_bf16 v[126:129], v[156:159], v[188:191], v[126:129]
	v_mfma_f32_16x16x32_bf16 v[122:125], v[164:167], v[188:191], v[122:125]
	v_mfma_f32_16x16x32_bf16 v[110:113], v[156:159], v[196:199], v[110:113]
	v_mfma_f32_16x16x32_bf16 v[106:109], v[164:167], v[196:199], v[106:109]
	v_mfma_f32_16x16x32_bf16 v[94:97], v[156:159], v[204:207], v[94:97]
	v_mfma_f32_16x16x32_bf16 v[90:93], v[164:167], v[204:207], v[90:93]
	v_mfma_f32_16x16x32_bf16 v[78:81], v[156:159], v[212:215], v[78:81]
	v_mfma_f32_16x16x32_bf16 v[74:77], v[164:167], v[212:215], v[74:77]
	v_mfma_f32_16x16x32_bf16 v[118:121], v[168:171], v[184:187], v[118:121]
	v_mfma_f32_16x16x32_bf16 v[114:117], v[176:179], v[184:187], v[114:117]
	v_mfma_f32_16x16x32_bf16 v[102:105], v[168:171], v[192:195], v[102:105]
	v_mfma_f32_16x16x32_bf16 v[98:101], v[176:179], v[192:195], v[98:101]
	v_mfma_f32_16x16x32_bf16 v[86:89], v[168:171], v[200:203], v[86:89]
	v_mfma_f32_16x16x32_bf16 v[82:85], v[176:179], v[200:203], v[82:85]
	v_mfma_f32_16x16x32_bf16 v[70:73], v[168:171], v[208:211], v[70:73]
	v_mfma_f32_16x16x32_bf16 v[66:69], v[176:179], v[208:211], v[66:69]
	v_mfma_f32_16x16x32_bf16 v[118:121], v[172:175], v[188:191], v[118:121]
	v_mfma_f32_16x16x32_bf16 v[114:117], v[180:183], v[188:191], v[114:117]
	v_mfma_f32_16x16x32_bf16 v[102:105], v[172:175], v[196:199], v[102:105]
	v_mfma_f32_16x16x32_bf16 v[98:101], v[180:183], v[196:199], v[98:101]
	v_mfma_f32_16x16x32_bf16 v[86:89], v[172:175], v[204:207], v[86:89]
	v_mfma_f32_16x16x32_bf16 v[82:85], v[180:183], v[204:207], v[82:85]
	v_mfma_f32_16x16x32_bf16 v[70:73], v[172:175], v[212:215], v[70:73]
	v_mfma_f32_16x16x32_bf16 v[66:69], v[180:183], v[212:215], v[66:69]
	s_setprio 0
	s_barrier
	s_add_i32 s26, s49, s30
	v_lshl_add_u64 v[216:217], v[216:217], 0, s[8:9]
	s_mov_b32 m0, s26
	ds_read_b128 v[184:187], v150 offset:49152
	ds_read_b128 v[188:191], v150 offset:50176
	ds_read_b128 v[192:195], v150 offset:51200
	ds_read_b128 v[196:199], v150 offset:52224
	ds_read_b128 v[200:203], v150 offset:53248
	ds_read_b128 v[204:207], v150 offset:54272
	ds_read_b128 v[208:211], v150 offset:55296
	ds_read_b128 v[212:215], v150 offset:56320
	global_load_lds_dwordx4 v[216:217], off
	s_add_i32 m0, s26, 0x2000
	s_add_u32 s24, s24, 0x100080
	v_lshl_add_u64 v[216:217], v[218:219], 0, s[8:9]
	s_addc_u32 s25, s25, 0
	s_add_i32 s26, s50, s30
	global_load_lds_dwordx4 v[216:217], off
	v_lshl_add_u64 v[216:217], s[24:25], 0, v[134:135]
	s_mov_b32 m0, s26
	s_nop 0
	global_load_lds_dwordx4 v[216:217], off
	v_lshl_add_u64 v[216:217], s[24:25], 0, v[130:131]
	s_add_i32 m0, s26, 0x2000
	s_nop 0
	global_load_lds_dwordx4 v[216:217], off
	v_lshl_add_u64 v[216:217], v[220:221], 0, s[8:9]
	s_mov_b32 m0, s37
	s_nop 0
	global_load_lds_dwordx4 v[216:217], off
	v_lshl_add_u64 v[216:217], v[222:223], 0, s[8:9]
	s_mov_b32 m0, s40
	s_nop 0
	global_load_lds_dwordx4 v[216:217], off
	s_waitcnt vmcnt(8)
	s_waitcnt lgkmcnt(0)
	s_barrier
	s_setprio 1
	s_waitcnt lgkmcnt(0)
	v_mfma_f32_16x16x32_bf16 v[62:65], v[152:155], v[184:187], v[62:65]
	v_mfma_f32_16x16x32_bf16 v[58:61], v[160:163], v[184:187], v[58:61]
	v_mfma_f32_16x16x32_bf16 v[46:49], v[152:155], v[192:195], v[46:49]
	v_mfma_f32_16x16x32_bf16 v[42:45], v[160:163], v[192:195], v[42:45]
	v_mfma_f32_16x16x32_bf16 v[30:33], v[152:155], v[200:203], v[30:33]
	v_mfma_f32_16x16x32_bf16 v[26:29], v[160:163], v[200:203], v[26:29]
	v_mfma_f32_16x16x32_bf16 v[22:25], v[152:155], v[208:211], v[22:25]
	v_mfma_f32_16x16x32_bf16 v[18:21], v[160:163], v[208:211], v[18:21]
	v_mfma_f32_16x16x32_bf16 v[62:65], v[156:159], v[188:191], v[62:65]
	v_mfma_f32_16x16x32_bf16 v[58:61], v[164:167], v[188:191], v[58:61]
	v_mfma_f32_16x16x32_bf16 v[46:49], v[156:159], v[196:199], v[46:49]
	v_mfma_f32_16x16x32_bf16 v[42:45], v[164:167], v[196:199], v[42:45]
	v_mfma_f32_16x16x32_bf16 v[30:33], v[156:159], v[204:207], v[30:33]
	v_mfma_f32_16x16x32_bf16 v[26:29], v[164:167], v[204:207], v[26:29]
	v_mfma_f32_16x16x32_bf16 v[22:25], v[156:159], v[212:215], v[22:25]
	v_mfma_f32_16x16x32_bf16 v[18:21], v[164:167], v[212:215], v[18:21]
	v_mfma_f32_16x16x32_bf16 v[54:57], v[168:171], v[184:187], v[54:57]
	v_mfma_f32_16x16x32_bf16 v[50:53], v[176:179], v[184:187], v[50:53]
	v_mfma_f32_16x16x32_bf16 v[38:41], v[168:171], v[192:195], v[38:41]
	v_mfma_f32_16x16x32_bf16 v[34:37], v[176:179], v[192:195], v[34:37]
	v_mfma_f32_16x16x32_bf16 v[14:17], v[168:171], v[200:203], v[14:17]
	v_mfma_f32_16x16x32_bf16 v[10:13], v[176:179], v[200:203], v[10:13]
	v_mfma_f32_16x16x32_bf16 v[6:9], v[168:171], v[208:211], v[6:9]
	v_mfma_f32_16x16x32_bf16 v[2:5], v[176:179], v[208:211], v[2:5]
	v_mfma_f32_16x16x32_bf16 v[54:57], v[172:175], v[188:191], v[54:57]
	v_mfma_f32_16x16x32_bf16 v[50:53], v[180:183], v[188:191], v[50:53]
	v_mfma_f32_16x16x32_bf16 v[38:41], v[172:175], v[196:199], v[38:41]
	v_mfma_f32_16x16x32_bf16 v[34:37], v[180:183], v[196:199], v[34:37]
	v_mfma_f32_16x16x32_bf16 v[14:17], v[172:175], v[204:207], v[14:17]
	v_mfma_f32_16x16x32_bf16 v[10:13], v[180:183], v[204:207], v[10:13]
	v_mfma_f32_16x16x32_bf16 v[6:9], v[172:175], v[212:215], v[6:9]
	v_mfma_f32_16x16x32_bf16 v[2:5], v[180:183], v[212:215], v[2:5]
	s_setprio 0
	s_barrier
	s_add_i32 s48, s48, 2
	s_add_u32 s22, s22, 0x100
	s_addc_u32 s23, s23, 0
	s_add_u32 s46, s46, 0x100
	s_addc_u32 s47, s47, 0
	s_cmp_lt_u32 s48, 62
	s_cbranch_scc1 .LBB0_1103
	s_nop 0
	s_nop 0
	s_nop 0
	s_nop 0
	s_nop 0
	s_nop 0
	s_nop 0
	s_nop 0
	s_andn2_b64 vcc, exec, s[10:11]
	s_cbranch_vccnz .LBB0_1106
	s_barrier

.LBB0_1262:
	ds_read_b128 v[50:53], v181
	ds_read_b128 v[54:57], v181 offset:1024
	ds_read_b128 v[138:141], v181 offset:2048
	ds_read_b128 v[142:145], v181 offset:3072
	ds_read_b128 v[168:171], v185
	ds_read_b128 v[174:177], v185 offset:1024
	ds_read_b128 v[190:193], v185 offset:2048
	ds_read_b128 v[194:197], v185 offset:3072
	s_add_u32 s28, s26, 0xfff80080
	s_addc_u32 s29, s27, -1
	s_cmp_eq_u32 s54, 28
	s_cselect_b32 s31, s19, s29
	s_cselect_b32 s30, s50, s28
	s_cselect_b32 s29, s17, s53
	s_cselect_b32 s28, s51, s52
	v_lshl_add_u64 v[178:179], s[26:27], 0, v[158:159]
	s_add_i32 m0, s37, 0xc000
	ds_read_b128 v[198:201], v189
	ds_read_b128 v[202:205], v189 offset:1024
	ds_read_b128 v[206:209], v189 offset:2048
	ds_read_b128 v[210:213], v189 offset:3072
	ds_read_b128 v[214:217], v189 offset:4096
	ds_read_b128 v[218:221], v189 offset:5120
	ds_read_b128 v[222:225], v189 offset:6144
	ds_read_b128 v[226:229], v189 offset:7168
	global_load_lds_dwordx4 v[178:179], off
	v_lshl_add_u64 v[178:179], s[26:27], 0, v[160:161]
	s_add_i32 m0, s37, 0xe000
	s_nop 0
	global_load_lds_dwordx4 v[178:179], off
	s_waitcnt vmcnt(8)
	s_waitcnt lgkmcnt(0)
	s_barrier
	s_setprio 1
	s_waitcnt lgkmcnt(0)
	v_mfma_i32_16x16x64_i8 v[134:137], v[50:53], v[198:201], v[134:137]
	v_mfma_i32_16x16x64_i8 v[130:133], v[138:141], v[198:201], v[130:133]
	v_mfma_i32_16x16x64_i8 v[118:121], v[50:53], v[206:209], v[118:121]
	v_mfma_i32_16x16x64_i8 v[114:117], v[138:141], v[206:209], v[114:117]
	v_mfma_i32_16x16x64_i8 v[102:105], v[50:53], v[214:217], v[102:105]
	v_mfma_i32_16x16x64_i8 v[98:101], v[138:141], v[214:217], v[98:101]
	v_mfma_i32_16x16x64_i8 v[86:89], v[50:53], v[222:225], v[86:89]
	v_mfma_i32_16x16x64_i8 v[82:85], v[138:141], v[222:225], v[82:85]
	v_mfma_i32_16x16x64_i8 v[134:137], v[54:57], v[202:205], v[134:137]
	v_mfma_i32_16x16x64_i8 v[130:133], v[142:145], v[202:205], v[130:133]
	v_mfma_i32_16x16x64_i8 v[118:121], v[54:57], v[210:213], v[118:121]
	v_mfma_i32_16x16x64_i8 v[114:117], v[142:145], v[210:213], v[114:117]
	v_mfma_i32_16x16x64_i8 v[102:105], v[54:57], v[218:221], v[102:105]
	v_mfma_i32_16x16x64_i8 v[98:101], v[142:145], v[218:221], v[98:101]
	v_mfma_i32_16x16x64_i8 v[86:89], v[54:57], v[226:229], v[86:89]
	v_mfma_i32_16x16x64_i8 v[82:85], v[142:145], v[226:229], v[82:85]
	v_mfma_i32_16x16x64_i8 v[126:129], v[168:171], v[198:201], v[126:129]
	v_mfma_i32_16x16x64_i8 v[122:125], v[190:193], v[198:201], v[122:125]
	v_mfma_i32_16x16x64_i8 v[110:113], v[168:171], v[206:209], v[110:113]
	v_mfma_i32_16x16x64_i8 v[106:109], v[190:193], v[206:209], v[106:109]
	v_mfma_i32_16x16x64_i8 v[94:97], v[168:171], v[214:217], v[94:97]
	v_mfma_i32_16x16x64_i8 v[90:93], v[190:193], v[214:217], v[90:93]
	v_mfma_i32_16x16x64_i8 v[78:81], v[168:171], v[222:225], v[78:81]
	v_mfma_i32_16x16x64_i8 v[74:77], v[190:193], v[222:225], v[74:77]
	v_mfma_i32_16x16x64_i8 v[126:129], v[174:177], v[202:205], v[126:129]
	v_mfma_i32_16x16x64_i8 v[122:125], v[194:197], v[202:205], v[122:125]
	v_mfma_i32_16x16x64_i8 v[110:113], v[174:177], v[210:213], v[110:113]
	v_mfma_i32_16x16x64_i8 v[106:109], v[194:197], v[210:213], v[106:109]
	v_mfma_i32_16x16x64_i8 v[94:97], v[174:177], v[218:221], v[94:97]
	v_mfma_i32_16x16x64_i8 v[90:93], v[194:197], v[218:221], v[90:93]
	v_mfma_i32_16x16x64_i8 v[78:81], v[174:177], v[226:229], v[78:81]
	v_mfma_i32_16x16x64_i8 v[74:77], v[194:197], v[226:229], v[74:77]
	s_setprio 0
	s_barrier
	s_add_i32 s55, s47, s35
	v_lshl_add_u64 v[178:179], s[28:29], 0, v[150:151]
	s_mov_b32 m0, s55
	ds_read_b128 v[198:201], v189 offset:16384
	ds_read_b128 v[202:205], v189 offset:17408
	ds_read_b128 v[206:209], v189 offset:18432
	ds_read_b128 v[210:213], v189 offset:19456
	ds_read_b128 v[214:217], v189 offset:20480
	ds_read_b128 v[218:221], v189 offset:21504
	ds_read_b128 v[222:225], v189 offset:22528
	ds_read_b128 v[226:229], v189 offset:23552
	global_load_lds_dwordx4 v[178:179], off
	s_add_i32 m0, s55, 0x2000
	s_add_u32 s56, s28, 0x80000
	v_lshl_add_u64 v[182:183], s[28:29], 0, v[146:147]
	s_addc_u32 s57, s29, 0
	s_add_i32 s55, s48, s35
	global_load_lds_dwordx4 v[182:183], off
	v_lshl_add_u64 v[186:187], s[56:57], 0, v[150:151]
	s_mov_b32 m0, s55
	v_lshl_add_u64 v[230:231], s[30:31], 0, v[148:149]
	global_load_lds_dwordx4 v[186:187], off
	v_lshl_add_u64 v[186:187], s[56:57], 0, v[146:147]
	s_add_i32 m0, s55, 0x2000
	s_nop 0
	global_load_lds_dwordx4 v[186:187], off
	v_lshl_add_u64 v[186:187], s[30:31], 0, v[152:153]
	s_mov_b32 m0, s37
	s_nop 0
	global_load_lds_dwordx4 v[186:187], off
	s_mov_b32 m0, s40
	s_nop 0
	global_load_lds_dwordx4 v[230:231], off
	s_waitcnt vmcnt(8)
	s_waitcnt lgkmcnt(0)
	s_barrier
	s_setprio 1
	s_waitcnt lgkmcnt(0)
	v_mfma_i32_16x16x64_i8 v[70:73], v[50:53], v[198:201], v[70:73]
	v_mfma_i32_16x16x64_i8 v[66:69], v[138:141], v[198:201], v[66:69]
	v_mfma_i32_16x16x64_i8 v[46:49], v[50:53], v[206:209], v[46:49]
	v_mfma_i32_16x16x64_i8 v[42:45], v[138:141], v[206:209], v[42:45]
	v_mfma_i32_16x16x64_i8 v[30:33], v[50:53], v[214:217], v[30:33]
	v_mfma_i32_16x16x64_i8 v[26:29], v[138:141], v[214:217], v[26:29]
	v_mfma_i32_16x16x64_i8 v[14:17], v[50:53], v[222:225], v[14:17]
	v_mfma_i32_16x16x64_i8 v[10:13], v[138:141], v[222:225], v[10:13]
	v_mfma_i32_16x16x64_i8 v[70:73], v[54:57], v[202:205], v[70:73]
	v_mfma_i32_16x16x64_i8 v[66:69], v[142:145], v[202:205], v[66:69]
	v_mfma_i32_16x16x64_i8 v[46:49], v[54:57], v[210:213], v[46:49]
	v_mfma_i32_16x16x64_i8 v[42:45], v[142:145], v[210:213], v[42:45]
	v_mfma_i32_16x16x64_i8 v[30:33], v[54:57], v[218:221], v[30:33]
	v_mfma_i32_16x16x64_i8 v[26:29], v[142:145], v[218:221], v[26:29]
	v_mfma_i32_16x16x64_i8 v[14:17], v[54:57], v[226:229], v[14:17]
	v_mfma_i32_16x16x64_i8 v[10:13], v[142:145], v[226:229], v[10:13]
	v_mfma_i32_16x16x64_i8 v[38:41], v[168:171], v[206:209], v[38:41]
	v_mfma_i32_16x16x64_i8 v[34:37], v[190:193], v[206:209], v[34:37]
	v_mfma_i32_16x16x64_i8 v[22:25], v[168:171], v[214:217], v[22:25]
	v_mfma_i32_16x16x64_i8 v[18:21], v[190:193], v[214:217], v[18:21]
	v_mfma_i32_16x16x64_i8 v[6:9], v[168:171], v[222:225], v[6:9]
	v_mfma_i32_16x16x64_i8 v[2:5], v[190:193], v[222:225], v[2:5]
	v_mfma_i32_16x16x64_i8 v[50:53], v[168:171], v[198:201], v[62:65]
	v_mfma_i32_16x16x64_i8 v[54:57], v[190:193], v[198:201], v[58:61]
	v_mfma_i32_16x16x64_i8 v[38:41], v[174:177], v[210:213], v[38:41]
	v_mfma_i32_16x16x64_i8 v[34:37], v[194:197], v[210:213], v[34:37]
	v_mfma_i32_16x16x64_i8 v[22:25], v[174:177], v[218:221], v[22:25]
	v_mfma_i32_16x16x64_i8 v[18:21], v[194:197], v[218:221], v[18:21]
	v_mfma_i32_16x16x64_i8 v[6:9], v[174:177], v[226:229], v[6:9]
	v_mfma_i32_16x16x64_i8 v[2:5], v[194:197], v[226:229], v[2:5]
	v_mfma_i32_16x16x64_i8 v[50:53], v[174:177], v[202:205], v[50:53]
	v_mfma_i32_16x16x64_i8 v[54:57], v[194:197], v[202:205], v[54:57]
	s_setprio 0
	s_barrier
	s_add_i32 s55, 0, 0x18000
	s_add_i32 s56, 0, 0x1c000
	v_add_u32_e32 v142, s55, v167
	v_add_u32_e32 v154, s56, v167
	ds_read_b128 v[58:61], v142
	ds_read_b128 v[62:65], v142 offset:1024
	ds_read_b128 v[138:141], v142 offset:2048
	ds_read_b128 v[142:145], v142 offset:3072
	ds_read_b128 v[168:171], v154
	ds_read_b128 v[174:177], v154 offset:1024
	ds_read_b128 v[190:193], v154 offset:2048
	ds_read_b128 v[194:197], v154 offset:3072
	s_add_u32 s30, s30, 0x80000
	s_addc_u32 s31, s31, 0
	s_mov_b32 m0, s41
	v_lshl_add_u64 v[232:233], s[30:31], 0, v[152:153]
	ds_read_b128 v[198:201], v189 offset:32768
	ds_read_b128 v[202:205], v189 offset:33792
	ds_read_b128 v[206:209], v189 offset:34816
	ds_read_b128 v[210:213], v189 offset:35840
	ds_read_b128 v[214:217], v189 offset:36864
	ds_read_b128 v[218:221], v189 offset:37888
	ds_read_b128 v[222:225], v189 offset:38912
	ds_read_b128 v[226:229], v189 offset:39936
	global_load_lds_dwordx4 v[232:233], off
	v_lshl_add_u64 v[232:233], s[30:31], 0, v[148:149]
	s_mov_b32 m0, s42
	s_nop 0
	global_load_lds_dwordx4 v[232:233], off
	s_waitcnt vmcnt(8)
	s_waitcnt lgkmcnt(0)
	s_barrier
	s_setprio 1
	s_waitcnt lgkmcnt(0)
	v_mfma_i32_16x16x64_i8 v[134:137], v[58:61], v[198:201], v[134:137]
	v_mfma_i32_16x16x64_i8 v[130:133], v[138:141], v[198:201], v[130:133]
	v_mfma_i32_16x16x64_i8 v[118:121], v[58:61], v[206:209], v[118:121]
	v_mfma_i32_16x16x64_i8 v[114:117], v[138:141], v[206:209], v[114:117]
	v_mfma_i32_16x16x64_i8 v[102:105], v[58:61], v[214:217], v[102:105]
	v_mfma_i32_16x16x64_i8 v[98:101], v[138:141], v[214:217], v[98:101]
	v_mfma_i32_16x16x64_i8 v[86:89], v[58:61], v[222:225], v[86:89]
	v_mfma_i32_16x16x64_i8 v[82:85], v[138:141], v[222:225], v[82:85]
	v_mfma_i32_16x16x64_i8 v[134:137], v[62:65], v[202:205], v[134:137]
	v_mfma_i32_16x16x64_i8 v[130:133], v[142:145], v[202:205], v[130:133]
	v_mfma_i32_16x16x64_i8 v[118:121], v[62:65], v[210:213], v[118:121]
	v_mfma_i32_16x16x64_i8 v[114:117], v[142:145], v[210:213], v[114:117]
	v_mfma_i32_16x16x64_i8 v[102:105], v[62:65], v[218:221], v[102:105]
	v_mfma_i32_16x16x64_i8 v[98:101], v[142:145], v[218:221], v[98:101]
	v_mfma_i32_16x16x64_i8 v[86:89], v[62:65], v[226:229], v[86:89]
	v_mfma_i32_16x16x64_i8 v[82:85], v[142:145], v[226:229], v[82:85]
	v_mfma_i32_16x16x64_i8 v[126:129], v[168:171], v[198:201], v[126:129]
	v_mfma_i32_16x16x64_i8 v[122:125], v[190:193], v[198:201], v[122:125]
	v_mfma_i32_16x16x64_i8 v[110:113], v[168:171], v[206:209], v[110:113]
	v_mfma_i32_16x16x64_i8 v[106:109], v[190:193], v[206:209], v[106:109]
	v_mfma_i32_16x16x64_i8 v[94:97], v[168:171], v[214:217], v[94:97]
	v_mfma_i32_16x16x64_i8 v[90:93], v[190:193], v[214:217], v[90:93]
	v_mfma_i32_16x16x64_i8 v[78:81], v[168:171], v[222:225], v[78:81]
	v_mfma_i32_16x16x64_i8 v[74:77], v[190:193], v[222:225], v[74:77]
	v_mfma_i32_16x16x64_i8 v[126:129], v[174:177], v[202:205], v[126:129]
	v_mfma_i32_16x16x64_i8 v[122:125], v[194:197], v[202:205], v[122:125]
	v_mfma_i32_16x16x64_i8 v[110:113], v[174:177], v[210:213], v[110:113]
	v_mfma_i32_16x16x64_i8 v[106:109], v[194:197], v[210:213], v[106:109]
	v_mfma_i32_16x16x64_i8 v[94:97], v[174:177], v[218:221], v[94:97]
	v_mfma_i32_16x16x64_i8 v[90:93], v[194:197], v[218:221], v[90:93]
	v_mfma_i32_16x16x64_i8 v[78:81], v[174:177], v[226:229], v[78:81]
	v_mfma_i32_16x16x64_i8 v[74:77], v[194:197], v[226:229], v[74:77]
	s_setprio 0
	s_barrier
	s_add_i32 s30, s55, s35
	v_lshl_add_u64 v[178:179], v[178:179], 0, s[12:13]
	s_mov_b32 m0, s30
	ds_read_b128 v[198:201], v189 offset:49152
	ds_read_b128 v[202:205], v189 offset:50176
	ds_read_b128 v[206:209], v189 offset:51200
	ds_read_b128 v[210:213], v189 offset:52224
	ds_read_b128 v[214:217], v189 offset:53248
	ds_read_b128 v[218:221], v189 offset:54272
	ds_read_b128 v[222:225], v189 offset:55296
	ds_read_b128 v[226:229], v189 offset:56320
	global_load_lds_dwordx4 v[178:179], off
	s_add_i32 m0, s30, 0x2000
	s_add_u32 s28, s28, 0x80080
	v_lshl_add_u64 v[178:179], v[182:183], 0, s[12:13]
	s_addc_u32 s29, s29, 0
	s_add_i32 s30, s56, s35
	global_load_lds_dwordx4 v[178:179], off
	v_lshl_add_u64 v[178:179], s[28:29], 0, v[150:151]
	s_mov_b32 m0, s30
	s_nop 0
	global_load_lds_dwordx4 v[178:179], off
	v_lshl_add_u64 v[178:179], s[28:29], 0, v[146:147]
	s_add_i32 m0, s30, 0x2000
	s_nop 0
	global_load_lds_dwordx4 v[178:179], off
	v_lshl_add_u64 v[178:179], v[186:187], 0, s[12:13]
	s_mov_b32 m0, s44
	s_nop 0
	global_load_lds_dwordx4 v[178:179], off
	v_lshl_add_u64 v[178:179], v[230:231], 0, s[12:13]
	s_mov_b32 m0, s45
	s_nop 0
	global_load_lds_dwordx4 v[178:179], off
	s_waitcnt vmcnt(8)
	s_waitcnt lgkmcnt(0)
	s_barrier
	s_setprio 1
	s_waitcnt lgkmcnt(0)
	v_mfma_i32_16x16x64_i8 v[70:73], v[58:61], v[198:201], v[70:73]
	v_mfma_i32_16x16x64_i8 v[66:69], v[138:141], v[198:201], v[66:69]
	v_mfma_i32_16x16x64_i8 v[46:49], v[58:61], v[206:209], v[46:49]
	v_mfma_i32_16x16x64_i8 v[42:45], v[138:141], v[206:209], v[42:45]
	v_mfma_i32_16x16x64_i8 v[30:33], v[58:61], v[214:217], v[30:33]
	v_mfma_i32_16x16x64_i8 v[26:29], v[138:141], v[214:217], v[26:29]
	v_mfma_i32_16x16x64_i8 v[14:17], v[58:61], v[222:225], v[14:17]
	v_mfma_i32_16x16x64_i8 v[10:13], v[138:141], v[222:225], v[10:13]
	v_mfma_i32_16x16x64_i8 v[70:73], v[62:65], v[202:205], v[70:73]
	v_mfma_i32_16x16x64_i8 v[66:69], v[142:145], v[202:205], v[66:69]
	v_mfma_i32_16x16x64_i8 v[46:49], v[62:65], v[210:213], v[46:49]
	v_mfma_i32_16x16x64_i8 v[42:45], v[142:145], v[210:213], v[42:45]
	v_mfma_i32_16x16x64_i8 v[30:33], v[62:65], v[218:221], v[30:33]
	v_mfma_i32_16x16x64_i8 v[26:29], v[142:145], v[218:221], v[26:29]
	v_mfma_i32_16x16x64_i8 v[14:17], v[62:65], v[226:229], v[14:17]
	v_mfma_i32_16x16x64_i8 v[10:13], v[142:145], v[226:229], v[10:13]
	v_mfma_i32_16x16x64_i8 v[50:53], v[168:171], v[198:201], v[50:53]
	v_mfma_i32_16x16x64_i8 v[62:65], v[174:177], v[202:205], v[50:53]
	v_mfma_i32_16x16x64_i8 v[50:53], v[190:193], v[198:201], v[54:57]
	v_mfma_i32_16x16x64_i8 v[38:41], v[168:171], v[206:209], v[38:41]
	v_mfma_i32_16x16x64_i8 v[34:37], v[190:193], v[206:209], v[34:37]
	v_mfma_i32_16x16x64_i8 v[22:25], v[168:171], v[214:217], v[22:25]
	v_mfma_i32_16x16x64_i8 v[18:21], v[190:193], v[214:217], v[18:21]
	v_mfma_i32_16x16x64_i8 v[6:9], v[168:171], v[222:225], v[6:9]
	v_mfma_i32_16x16x64_i8 v[2:5], v[190:193], v[222:225], v[2:5]
	v_mfma_i32_16x16x64_i8 v[58:61], v[194:197], v[202:205], v[50:53]
	v_mfma_i32_16x16x64_i8 v[38:41], v[174:177], v[210:213], v[38:41]
	v_mfma_i32_16x16x64_i8 v[34:37], v[194:197], v[210:213], v[34:37]
	v_mfma_i32_16x16x64_i8 v[22:25], v[174:177], v[218:221], v[22:25]
	v_mfma_i32_16x16x64_i8 v[18:21], v[194:197], v[218:221], v[18:21]
	v_mfma_i32_16x16x64_i8 v[6:9], v[174:177], v[226:229], v[6:9]
	v_mfma_i32_16x16x64_i8 v[2:5], v[194:197], v[226:229], v[2:5]
	s_setprio 0
	s_barrier
	s_add_i32 s54, s54, 2
	s_add_u32 s26, s26, 0x100
	s_addc_u32 s27, s27, 0
	s_add_u32 s52, s52, 0x100
	s_addc_u32 s53, s53, 0
	s_cmp_lt_u32 s54, 30
	s_cbranch_scc1 .LBB0_1262
	s_nop 0
	s_nop 0
	s_nop 0
	s_nop 0
	s_nop 0
	s_nop 0
	s_nop 0
	s_nop 0
	s_andn2_b64 vcc, exec, s[14:15]
	s_cbranch_vccnz .LBB0_1265
	s_barrier

.LBB0_1402:
	ds_read_b128 v[124:127], v173
	ds_read_b128 v[128:131], v173 offset:1024
	ds_read_b128 v[136:139], v173 offset:2048
	ds_read_b128 v[140:143], v173 offset:3072
	ds_read_b128 v[162:165], v174
	ds_read_b128 v[166:169], v174 offset:1024
	ds_read_b128 v[176:179], v174 offset:2048
	ds_read_b128 v[180:183], v174 offset:3072
	s_add_u32 s20, s18, 0xffea8080
	s_addc_u32 s21, s19, -1
	s_cmpk_eq_i32 s44, 0x52
	s_cselect_b32 s23, s5, s21
	s_cselect_b32 s22, s4, s20
	s_cselect_b32 s21, s17, s43
	s_cselect_b32 s20, s16, s42
	v_lshl_add_u64 v[216:217], s[18:19], 0, v[154:155]
	s_add_i32 m0, s27, 0xc000
	ds_read_b128 v[184:187], v175
	ds_read_b128 v[188:191], v175 offset:1024
	ds_read_b128 v[192:195], v175 offset:2048
	ds_read_b128 v[196:199], v175 offset:3072
	ds_read_b128 v[200:203], v175 offset:4096
	ds_read_b128 v[204:207], v175 offset:5120
	ds_read_b128 v[208:211], v175 offset:6144
	ds_read_b128 v[212:215], v175 offset:7168
	global_load_lds_dwordx4 v[216:217], off
	v_lshl_add_u64 v[216:217], s[18:19], 0, v[156:157]
	s_add_i32 m0, s27, 0xe000
	s_nop 0
	global_load_lds_dwordx4 v[216:217], off
	s_waitcnt vmcnt(8)
	s_waitcnt lgkmcnt(0)
	s_barrier
	s_setprio 1
	s_waitcnt lgkmcnt(0)
	v_mfma_i32_16x16x64_i8 v[132:135], v[124:127], v[184:187], v[132:135]
	v_mfma_i32_16x16x64_i8 v[120:123], v[136:139], v[184:187], v[120:123]
	v_mfma_i32_16x16x64_i8 v[108:111], v[124:127], v[192:195], v[108:111]
	v_mfma_i32_16x16x64_i8 v[104:107], v[136:139], v[192:195], v[104:107]
	v_mfma_i32_16x16x64_i8 v[92:95], v[124:127], v[200:203], v[92:95]
	v_mfma_i32_16x16x64_i8 v[88:91], v[136:139], v[200:203], v[88:91]
	v_mfma_i32_16x16x64_i8 v[76:79], v[124:127], v[208:211], v[76:79]
	v_mfma_i32_16x16x64_i8 v[72:75], v[136:139], v[208:211], v[72:75]
	v_mfma_i32_16x16x64_i8 v[132:135], v[128:131], v[188:191], v[132:135]
	v_mfma_i32_16x16x64_i8 v[120:123], v[140:143], v[188:191], v[120:123]
	v_mfma_i32_16x16x64_i8 v[108:111], v[128:131], v[196:199], v[108:111]
	v_mfma_i32_16x16x64_i8 v[104:107], v[140:143], v[196:199], v[104:107]
	v_mfma_i32_16x16x64_i8 v[92:95], v[128:131], v[204:207], v[92:95]
	v_mfma_i32_16x16x64_i8 v[88:91], v[140:143], v[204:207], v[88:91]
	v_mfma_i32_16x16x64_i8 v[76:79], v[128:131], v[212:215], v[76:79]
	v_mfma_i32_16x16x64_i8 v[72:75], v[140:143], v[212:215], v[72:75]
	v_mfma_i32_16x16x64_i8 v[116:119], v[162:165], v[184:187], v[116:119]
	v_mfma_i32_16x16x64_i8 v[112:115], v[176:179], v[184:187], v[112:115]
	v_mfma_i32_16x16x64_i8 v[100:103], v[162:165], v[192:195], v[100:103]
	v_mfma_i32_16x16x64_i8 v[96:99], v[176:179], v[192:195], v[96:99]
	v_mfma_i32_16x16x64_i8 v[84:87], v[162:165], v[200:203], v[84:87]
	v_mfma_i32_16x16x64_i8 v[80:83], v[176:179], v[200:203], v[80:83]
	v_mfma_i32_16x16x64_i8 v[68:71], v[162:165], v[208:211], v[68:71]
	v_mfma_i32_16x16x64_i8 v[64:67], v[176:179], v[208:211], v[64:67]
	v_mfma_i32_16x16x64_i8 v[116:119], v[166:169], v[188:191], v[116:119]
	v_mfma_i32_16x16x64_i8 v[112:115], v[180:183], v[188:191], v[112:115]
	v_mfma_i32_16x16x64_i8 v[100:103], v[166:169], v[196:199], v[100:103]
	v_mfma_i32_16x16x64_i8 v[96:99], v[180:183], v[196:199], v[96:99]
	v_mfma_i32_16x16x64_i8 v[84:87], v[166:169], v[204:207], v[84:87]
	v_mfma_i32_16x16x64_i8 v[80:83], v[180:183], v[204:207], v[80:83]
	v_mfma_i32_16x16x64_i8 v[68:71], v[166:169], v[212:215], v[68:71]
	v_mfma_i32_16x16x64_i8 v[64:67], v[180:183], v[212:215], v[64:67]
	s_setprio 0
	s_barrier
	s_add_i32 s45, s36, s24
	v_lshl_add_u64 v[216:217], s[20:21], 0, v[148:149]
	s_mov_b32 m0, s45
	ds_read_b128 v[184:187], v175 offset:16384
	ds_read_b128 v[188:191], v175 offset:17408
	ds_read_b128 v[192:195], v175 offset:18432
	ds_read_b128 v[196:199], v175 offset:19456
	ds_read_b128 v[200:203], v175 offset:20480
	ds_read_b128 v[204:207], v175 offset:21504
	ds_read_b128 v[208:211], v175 offset:22528
	ds_read_b128 v[212:215], v175 offset:23552
	global_load_lds_dwordx4 v[216:217], off
	s_add_i32 m0, s45, 0x2000
	s_add_u32 s46, s20, 0x158000
	v_lshl_add_u64 v[218:219], s[20:21], 0, v[144:145]
	s_addc_u32 s47, s21, 0
	s_add_i32 s45, s37, s24
	global_load_lds_dwordx4 v[218:219], off
	v_lshl_add_u64 v[220:221], s[46:47], 0, v[148:149]
	s_mov_b32 m0, s45
	v_lshl_add_u64 v[222:223], s[22:23], 0, v[146:147]
	global_load_lds_dwordx4 v[220:221], off
	v_lshl_add_u64 v[220:221], s[46:47], 0, v[144:145]
	s_add_i32 m0, s45, 0x2000
	s_nop 0
	global_load_lds_dwordx4 v[220:221], off
	v_lshl_add_u64 v[220:221], s[22:23], 0, v[150:151]
	s_mov_b32 m0, s27
	s_nop 0
	global_load_lds_dwordx4 v[220:221], off
	s_mov_b32 m0, s28
	s_nop 0
	global_load_lds_dwordx4 v[222:223], off
	s_waitcnt vmcnt(8)
	s_waitcnt lgkmcnt(0)
	s_barrier
	s_setprio 1
	s_waitcnt lgkmcnt(0)
	v_mfma_i32_16x16x64_i8 v[60:63], v[124:127], v[184:187], v[60:63]
	v_mfma_i32_16x16x64_i8 v[56:59], v[136:139], v[184:187], v[56:59]
	v_mfma_i32_16x16x64_i8 v[44:47], v[124:127], v[192:195], v[44:47]
	v_mfma_i32_16x16x64_i8 v[40:43], v[136:139], v[192:195], v[40:43]
	v_mfma_i32_16x16x64_i8 v[28:31], v[124:127], v[200:203], v[28:31]
	v_mfma_i32_16x16x64_i8 v[24:27], v[136:139], v[200:203], v[24:27]
	v_mfma_i32_16x16x64_i8 v[12:15], v[124:127], v[208:211], v[12:15]
	v_mfma_i32_16x16x64_i8 v[8:11], v[136:139], v[208:211], v[8:11]
	v_mfma_i32_16x16x64_i8 v[60:63], v[128:131], v[188:191], v[60:63]
	v_mfma_i32_16x16x64_i8 v[56:59], v[140:143], v[188:191], v[56:59]
	v_mfma_i32_16x16x64_i8 v[44:47], v[128:131], v[196:199], v[44:47]
	v_mfma_i32_16x16x64_i8 v[40:43], v[140:143], v[196:199], v[40:43]
	v_mfma_i32_16x16x64_i8 v[28:31], v[128:131], v[204:207], v[28:31]
	v_mfma_i32_16x16x64_i8 v[24:27], v[140:143], v[204:207], v[24:27]
	v_mfma_i32_16x16x64_i8 v[12:15], v[128:131], v[212:215], v[12:15]
	v_mfma_i32_16x16x64_i8 v[8:11], v[140:143], v[212:215], v[8:11]
	v_mfma_i32_16x16x64_i8 v[52:55], v[162:165], v[184:187], v[52:55]
	v_mfma_i32_16x16x64_i8 v[48:51], v[176:179], v[184:187], v[48:51]
	v_mfma_i32_16x16x64_i8 v[36:39], v[162:165], v[192:195], v[36:39]
	v_mfma_i32_16x16x64_i8 v[32:35], v[176:179], v[192:195], v[32:35]
	v_mfma_i32_16x16x64_i8 v[20:23], v[162:165], v[200:203], v[20:23]
	v_mfma_i32_16x16x64_i8 v[16:19], v[176:179], v[200:203], v[16:19]
	v_mfma_i32_16x16x64_i8 v[4:7], v[162:165], v[208:211], v[4:7]
	v_mfma_i32_16x16x64_i8 v[0:3], v[176:179], v[208:211], v[0:3]
	v_mfma_i32_16x16x64_i8 v[52:55], v[166:169], v[188:191], v[52:55]
	v_mfma_i32_16x16x64_i8 v[48:51], v[180:183], v[188:191], v[48:51]
	v_mfma_i32_16x16x64_i8 v[36:39], v[166:169], v[196:199], v[36:39]
	v_mfma_i32_16x16x64_i8 v[32:35], v[180:183], v[196:199], v[32:35]
	v_mfma_i32_16x16x64_i8 v[20:23], v[166:169], v[204:207], v[20:23]
	v_mfma_i32_16x16x64_i8 v[16:19], v[180:183], v[204:207], v[16:19]
	v_mfma_i32_16x16x64_i8 v[4:7], v[166:169], v[212:215], v[4:7]
	v_mfma_i32_16x16x64_i8 v[0:3], v[180:183], v[212:215], v[0:3]
	s_setprio 0
	s_barrier
	s_add_i32 s45, 0, 0x18000
	s_add_i32 s46, 0, 0x1c000
	v_add_u32_e32 v140, s45, v171
	v_add_u32_e32 v152, s46, v171
	ds_read_b128 v[124:127], v140
	ds_read_b128 v[128:131], v140 offset:1024
	ds_read_b128 v[136:139], v140 offset:2048
	ds_read_b128 v[140:143], v140 offset:3072
	ds_read_b128 v[162:165], v152
	ds_read_b128 v[166:169], v152 offset:1024
	ds_read_b128 v[176:179], v152 offset:2048
	ds_read_b128 v[180:183], v152 offset:3072
	s_add_u32 s22, s22, 0x158000
	s_addc_u32 s23, s23, 0
	s_mov_b32 m0, s29
	v_lshl_add_u64 v[224:225], s[22:23], 0, v[150:151]
	ds_read_b128 v[184:187], v175 offset:32768
	ds_read_b128 v[188:191], v175 offset:33792
	ds_read_b128 v[192:195], v175 offset:34816
	ds_read_b128 v[196:199], v175 offset:35840
	ds_read_b128 v[200:203], v175 offset:36864
	ds_read_b128 v[204:207], v175 offset:37888
	ds_read_b128 v[208:211], v175 offset:38912
	ds_read_b128 v[212:215], v175 offset:39936
	global_load_lds_dwordx4 v[224:225], off
	v_lshl_add_u64 v[224:225], s[22:23], 0, v[146:147]
	s_mov_b32 m0, s30
	s_nop 0
	global_load_lds_dwordx4 v[224:225], off
	s_waitcnt vmcnt(8)
	s_waitcnt lgkmcnt(0)
	s_barrier
	s_setprio 1
	s_waitcnt lgkmcnt(0)
	v_mfma_i32_16x16x64_i8 v[132:135], v[124:127], v[184:187], v[132:135]
	v_mfma_i32_16x16x64_i8 v[120:123], v[136:139], v[184:187], v[120:123]
	v_mfma_i32_16x16x64_i8 v[108:111], v[124:127], v[192:195], v[108:111]
	v_mfma_i32_16x16x64_i8 v[104:107], v[136:139], v[192:195], v[104:107]
	v_mfma_i32_16x16x64_i8 v[92:95], v[124:127], v[200:203], v[92:95]
	v_mfma_i32_16x16x64_i8 v[88:91], v[136:139], v[200:203], v[88:91]
	v_mfma_i32_16x16x64_i8 v[76:79], v[124:127], v[208:211], v[76:79]
	v_mfma_i32_16x16x64_i8 v[72:75], v[136:139], v[208:211], v[72:75]
	v_mfma_i32_16x16x64_i8 v[132:135], v[128:131], v[188:191], v[132:135]
	v_mfma_i32_16x16x64_i8 v[120:123], v[140:143], v[188:191], v[120:123]
	v_mfma_i32_16x16x64_i8 v[108:111], v[128:131], v[196:199], v[108:111]
	v_mfma_i32_16x16x64_i8 v[104:107], v[140:143], v[196:199], v[104:107]
	v_mfma_i32_16x16x64_i8 v[92:95], v[128:131], v[204:207], v[92:95]
	v_mfma_i32_16x16x64_i8 v[88:91], v[140:143], v[204:207], v[88:91]
	v_mfma_i32_16x16x64_i8 v[76:79], v[128:131], v[212:215], v[76:79]
	v_mfma_i32_16x16x64_i8 v[72:75], v[140:143], v[212:215], v[72:75]
	v_mfma_i32_16x16x64_i8 v[116:119], v[162:165], v[184:187], v[116:119]
	v_mfma_i32_16x16x64_i8 v[112:115], v[176:179], v[184:187], v[112:115]
	v_mfma_i32_16x16x64_i8 v[100:103], v[162:165], v[192:195], v[100:103]
	v_mfma_i32_16x16x64_i8 v[96:99], v[176:179], v[192:195], v[96:99]
	v_mfma_i32_16x16x64_i8 v[84:87], v[162:165], v[200:203], v[84:87]
	v_mfma_i32_16x16x64_i8 v[80:83], v[176:179], v[200:203], v[80:83]
	v_mfma_i32_16x16x64_i8 v[68:71], v[162:165], v[208:211], v[68:71]
	v_mfma_i32_16x16x64_i8 v[64:67], v[176:179], v[208:211], v[64:67]
	v_mfma_i32_16x16x64_i8 v[116:119], v[166:169], v[188:191], v[116:119]
	v_mfma_i32_16x16x64_i8 v[112:115], v[180:183], v[188:191], v[112:115]
	v_mfma_i32_16x16x64_i8 v[100:103], v[166:169], v[196:199], v[100:103]
	v_mfma_i32_16x16x64_i8 v[96:99], v[180:183], v[196:199], v[96:99]
	v_mfma_i32_16x16x64_i8 v[84:87], v[166:169], v[204:207], v[84:87]
	v_mfma_i32_16x16x64_i8 v[80:83], v[180:183], v[204:207], v[80:83]
	v_mfma_i32_16x16x64_i8 v[68:71], v[166:169], v[212:215], v[68:71]
	v_mfma_i32_16x16x64_i8 v[64:67], v[180:183], v[212:215], v[64:67]
	s_setprio 0
	s_barrier
	s_add_i32 s22, s45, s24
	v_lshl_add_u64 v[216:217], v[216:217], 0, s[12:13]
	s_mov_b32 m0, s22
	ds_read_b128 v[184:187], v175 offset:49152
	ds_read_b128 v[188:191], v175 offset:50176
	ds_read_b128 v[192:195], v175 offset:51200
	ds_read_b128 v[196:199], v175 offset:52224
	ds_read_b128 v[200:203], v175 offset:53248
	ds_read_b128 v[204:207], v175 offset:54272
	ds_read_b128 v[208:211], v175 offset:55296
	ds_read_b128 v[212:215], v175 offset:56320
	global_load_lds_dwordx4 v[216:217], off
	s_add_i32 m0, s22, 0x2000
	s_add_u32 s20, s20, 0x158080
	v_lshl_add_u64 v[216:217], v[218:219], 0, s[12:13]
	s_addc_u32 s21, s21, 0
	s_add_i32 s22, s46, s24
	global_load_lds_dwordx4 v[216:217], off
	v_lshl_add_u64 v[216:217], s[20:21], 0, v[148:149]
	s_mov_b32 m0, s22
	s_nop 0
	global_load_lds_dwordx4 v[216:217], off
	v_lshl_add_u64 v[216:217], s[20:21], 0, v[144:145]
	s_add_i32 m0, s22, 0x2000
	s_nop 0
	global_load_lds_dwordx4 v[216:217], off
	v_lshl_add_u64 v[216:217], v[220:221], 0, s[12:13]
	s_mov_b32 m0, s33
	s_nop 0
	global_load_lds_dwordx4 v[216:217], off
	v_lshl_add_u64 v[216:217], v[222:223], 0, s[12:13]
	s_mov_b32 m0, s34
	s_nop 0
	global_load_lds_dwordx4 v[216:217], off
	s_waitcnt vmcnt(8)
	s_waitcnt lgkmcnt(0)
	s_barrier
	s_setprio 1
	s_waitcnt lgkmcnt(0)
	v_mfma_i32_16x16x64_i8 v[60:63], v[124:127], v[184:187], v[60:63]
	v_mfma_i32_16x16x64_i8 v[56:59], v[136:139], v[184:187], v[56:59]
	v_mfma_i32_16x16x64_i8 v[44:47], v[124:127], v[192:195], v[44:47]
	v_mfma_i32_16x16x64_i8 v[40:43], v[136:139], v[192:195], v[40:43]
	v_mfma_i32_16x16x64_i8 v[28:31], v[124:127], v[200:203], v[28:31]
	v_mfma_i32_16x16x64_i8 v[24:27], v[136:139], v[200:203], v[24:27]
	v_mfma_i32_16x16x64_i8 v[12:15], v[124:127], v[208:211], v[12:15]
	v_mfma_i32_16x16x64_i8 v[8:11], v[136:139], v[208:211], v[8:11]
	v_mfma_i32_16x16x64_i8 v[60:63], v[128:131], v[188:191], v[60:63]
	v_mfma_i32_16x16x64_i8 v[56:59], v[140:143], v[188:191], v[56:59]
	v_mfma_i32_16x16x64_i8 v[44:47], v[128:131], v[196:199], v[44:47]
	v_mfma_i32_16x16x64_i8 v[40:43], v[140:143], v[196:199], v[40:43]
	v_mfma_i32_16x16x64_i8 v[28:31], v[128:131], v[204:207], v[28:31]
	v_mfma_i32_16x16x64_i8 v[24:27], v[140:143], v[204:207], v[24:27]
	v_mfma_i32_16x16x64_i8 v[12:15], v[128:131], v[212:215], v[12:15]
	v_mfma_i32_16x16x64_i8 v[8:11], v[140:143], v[212:215], v[8:11]
	v_mfma_i32_16x16x64_i8 v[52:55], v[162:165], v[184:187], v[52:55]
	v_mfma_i32_16x16x64_i8 v[48:51], v[176:179], v[184:187], v[48:51]
	v_mfma_i32_16x16x64_i8 v[36:39], v[162:165], v[192:195], v[36:39]
	v_mfma_i32_16x16x64_i8 v[32:35], v[176:179], v[192:195], v[32:35]
	v_mfma_i32_16x16x64_i8 v[20:23], v[162:165], v[200:203], v[20:23]
	v_mfma_i32_16x16x64_i8 v[16:19], v[176:179], v[200:203], v[16:19]
	v_mfma_i32_16x16x64_i8 v[4:7], v[162:165], v[208:211], v[4:7]
	v_mfma_i32_16x16x64_i8 v[0:3], v[176:179], v[208:211], v[0:3]
	v_mfma_i32_16x16x64_i8 v[52:55], v[166:169], v[188:191], v[52:55]
	v_mfma_i32_16x16x64_i8 v[48:51], v[180:183], v[188:191], v[48:51]
	v_mfma_i32_16x16x64_i8 v[36:39], v[166:169], v[196:199], v[36:39]
	v_mfma_i32_16x16x64_i8 v[32:35], v[180:183], v[196:199], v[32:35]
	v_mfma_i32_16x16x64_i8 v[20:23], v[166:169], v[204:207], v[20:23]
	v_mfma_i32_16x16x64_i8 v[16:19], v[180:183], v[204:207], v[16:19]
	v_mfma_i32_16x16x64_i8 v[4:7], v[166:169], v[212:215], v[4:7]
	v_mfma_i32_16x16x64_i8 v[0:3], v[180:183], v[212:215], v[0:3]
	s_setprio 0
	s_barrier
	s_add_i32 s44, s44, 2
	s_add_u32 s18, s18, 0x100
	s_addc_u32 s19, s19, 0
	s_add_u32 s42, s42, 0x100
	s_addc_u32 s43, s43, 0
	s_cmpk_lt_u32 s44, 0x54
	s_cbranch_scc1 .LBB0_1402
	s_nop 0
	s_nop 0
	s_nop 0
	s_nop 0
	s_nop 0
	s_nop 0
	s_nop 0
	s_nop 0
	s_andn2_b64 vcc, exec, s[14:15]
	s_cbranch_vccnz .LBB0_1405
	s_barrier
